# diff attention: the two in-loop barrier waits no longer drain vmcnt (explicit counted waits cover the DMA)
# speedup vs baseline: 1.0016x; 1.0016x over previous
.LBB0_200:
	ds_read_b128 v[148:151], v169
	ds_read_b128 v[152:155], v169 offset:1024
	ds_read_b128 v[156:159], v169 offset:2048
	ds_read_b128 v[160:163], v169 offset:3072
	ds_read_b128 v[174:177], v170
	ds_read_b128 v[178:181], v170 offset:1024
	ds_read_b128 v[182:185], v170 offset:2048
	ds_read_b128 v[186:189], v170 offset:3072
	s_add_u32 s26, s6, 0xfff00800
	s_addc_u32 s27, s7, -1
	s_cmp_eq_u32 s34, 60
	s_cselect_b32 s29, s17, s27
	s_cselect_b32 s28, s23, s26
	s_cselect_b32 s27, s15, s31
	s_cselect_b32 s26, s25, s30
	v_lshl_add_u64 v[190:191], s[6:7], 0, v[138:139]
	s_add_i32 m0, s41, 0xc000
	s_nop 0
	global_load_lds_dwordx4 v[190:191], off
	v_lshl_add_u64 v[190:191], s[6:7], 0, v[140:141]
	s_add_i32 m0, s41, 0xe000
	s_nop 0
	global_load_lds_dwordx4 v[190:191], off
	ds_read_b128 v[190:193], v171
	ds_read_b128 v[194:197], v171 offset:1024
	ds_read_b128 v[198:201], v171 offset:2048
	ds_read_b128 v[202:205], v171 offset:3072
	ds_read_b128 v[206:209], v171 offset:4096
	ds_read_b128 v[210:213], v171 offset:5120
	ds_read_b128 v[214:217], v171 offset:6144
	ds_read_b128 v[218:221], v171 offset:7168
	s_waitcnt vmcnt(8)
	s_waitcnt lgkmcnt(0)
	s_barrier
	s_setprio 1
	s_waitcnt lgkmcnt(0)
	v_mfma_f32_16x16x32_bf16 v[124:127], v[148:151], v[190:193], v[124:127]
	v_mfma_f32_16x16x32_bf16 v[120:123], v[156:159], v[190:193], v[120:123]
	v_mfma_f32_16x16x32_bf16 v[116:119], v[148:151], v[198:201], v[116:119]
	v_mfma_f32_16x16x32_bf16 v[112:115], v[156:159], v[198:201], v[112:115]
	v_mfma_f32_16x16x32_bf16 v[108:111], v[148:151], v[206:209], v[108:111]
	v_mfma_f32_16x16x32_bf16 v[104:107], v[156:159], v[206:209], v[104:107]
	v_mfma_f32_16x16x32_bf16 v[100:103], v[148:151], v[214:217], v[100:103]
	v_mfma_f32_16x16x32_bf16 v[96:99], v[156:159], v[214:217], v[96:99]
	v_mfma_f32_16x16x32_bf16 v[124:127], v[152:155], v[194:197], v[124:127]
	v_mfma_f32_16x16x32_bf16 v[120:123], v[160:163], v[194:197], v[120:123]
	v_mfma_f32_16x16x32_bf16 v[116:119], v[152:155], v[202:205], v[116:119]
	v_mfma_f32_16x16x32_bf16 v[112:115], v[160:163], v[202:205], v[112:115]
	v_mfma_f32_16x16x32_bf16 v[108:111], v[152:155], v[210:213], v[108:111]
	v_mfma_f32_16x16x32_bf16 v[104:107], v[160:163], v[210:213], v[104:107]
	v_mfma_f32_16x16x32_bf16 v[100:103], v[152:155], v[218:221], v[100:103]
	v_mfma_f32_16x16x32_bf16 v[96:99], v[160:163], v[218:221], v[96:99]
	s_setprio 0
	s_setprio 1
	v_mfma_f32_16x16x32_bf16 v[60:63], v[174:177], v[190:193], v[60:63]
	v_mfma_f32_16x16x32_bf16 v[56:59], v[182:185], v[190:193], v[56:59]
	v_mfma_f32_16x16x32_bf16 v[52:55], v[174:177], v[198:201], v[52:55]
	v_mfma_f32_16x16x32_bf16 v[48:51], v[182:185], v[198:201], v[48:51]
	v_mfma_f32_16x16x32_bf16 v[44:47], v[174:177], v[206:209], v[44:47]
	v_mfma_f32_16x16x32_bf16 v[40:43], v[182:185], v[206:209], v[40:43]
	v_mfma_f32_16x16x32_bf16 v[36:39], v[174:177], v[214:217], v[36:39]
	v_mfma_f32_16x16x32_bf16 v[32:35], v[182:185], v[214:217], v[32:35]
	v_mfma_f32_16x16x32_bf16 v[60:63], v[178:181], v[194:197], v[60:63]
	v_mfma_f32_16x16x32_bf16 v[56:59], v[186:189], v[194:197], v[56:59]
	v_mfma_f32_16x16x32_bf16 v[52:55], v[178:181], v[202:205], v[52:55]
	v_mfma_f32_16x16x32_bf16 v[48:51], v[186:189], v[202:205], v[48:51]
	v_mfma_f32_16x16x32_bf16 v[44:47], v[178:181], v[210:213], v[44:47]
	v_mfma_f32_16x16x32_bf16 v[40:43], v[186:189], v[210:213], v[40:43]
	v_mfma_f32_16x16x32_bf16 v[36:39], v[178:181], v[218:221], v[36:39]
	v_mfma_f32_16x16x32_bf16 v[32:35], v[186:189], v[218:221], v[32:35]
	s_setprio 0
	s_barrier
	s_add_i32 s35, s55, s36
	v_lshl_add_u64 v[222:223], s[26:27], 0, v[130:131]
	s_mov_b32 m0, s35
	v_lshl_add_u64 v[224:225], s[26:27], 0, v[134:135]
	global_load_lds_dwordx4 v[222:223], off
	s_add_i32 m0, s35, 0x2000
	s_add_u32 s58, s26, 0x100000
	s_addc_u32 s59, s27, 0
	s_add_i32 s35, s56, s36
	global_load_lds_dwordx4 v[224:225], off
	v_lshl_add_u64 v[190:191], s[58:59], 0, v[130:131]
	s_mov_b32 m0, s35
	v_lshl_add_u64 v[226:227], s[28:29], 0, v[128:129]
	global_load_lds_dwordx4 v[190:191], off
	v_lshl_add_u64 v[190:191], s[58:59], 0, v[134:135]
	s_add_i32 m0, s35, 0x2000
	v_lshl_add_u64 v[228:229], s[28:29], 0, v[132:133]
	global_load_lds_dwordx4 v[190:191], off
	s_mov_b32 m0, s41
	s_nop 0
	global_load_lds_dwordx4 v[226:227], off
	s_mov_b32 m0, s42
	s_nop 0
	global_load_lds_dwordx4 v[228:229], off
	ds_read_b128 v[190:193], v171 offset:16384
	ds_read_b128 v[194:197], v171 offset:17408
	ds_read_b128 v[198:201], v171 offset:18432
	ds_read_b128 v[202:205], v171 offset:19456
	ds_read_b128 v[206:209], v171 offset:20480
	ds_read_b128 v[210:213], v171 offset:21504
	ds_read_b128 v[214:217], v171 offset:22528
	ds_read_b128 v[218:221], v171 offset:23552
	s_waitcnt vmcnt(8)
	s_waitcnt lgkmcnt(0)
	s_barrier
	s_setprio 1
	s_waitcnt lgkmcnt(0)
	v_mfma_f32_16x16x32_bf16 v[92:95], v[148:151], v[190:193], v[92:95]
	v_mfma_f32_16x16x32_bf16 v[88:91], v[156:159], v[190:193], v[88:91]
	v_mfma_f32_16x16x32_bf16 v[84:87], v[148:151], v[198:201], v[84:87]
	v_mfma_f32_16x16x32_bf16 v[80:83], v[156:159], v[198:201], v[80:83]
	v_mfma_f32_16x16x32_bf16 v[76:79], v[148:151], v[206:209], v[76:79]
	v_mfma_f32_16x16x32_bf16 v[72:75], v[156:159], v[206:209], v[72:75]
	v_mfma_f32_16x16x32_bf16 v[68:71], v[148:151], v[214:217], v[68:71]
	v_mfma_f32_16x16x32_bf16 v[64:67], v[156:159], v[214:217], v[64:67]
	v_mfma_f32_16x16x32_bf16 v[92:95], v[152:155], v[194:197], v[92:95]
	v_mfma_f32_16x16x32_bf16 v[88:91], v[160:163], v[194:197], v[88:91]
	v_mfma_f32_16x16x32_bf16 v[84:87], v[152:155], v[202:205], v[84:87]
	v_mfma_f32_16x16x32_bf16 v[80:83], v[160:163], v[202:205], v[80:83]
	v_mfma_f32_16x16x32_bf16 v[76:79], v[152:155], v[210:213], v[76:79]
	v_mfma_f32_16x16x32_bf16 v[72:75], v[160:163], v[210:213], v[72:75]
	v_mfma_f32_16x16x32_bf16 v[68:71], v[152:155], v[218:221], v[68:71]
	v_mfma_f32_16x16x32_bf16 v[64:67], v[160:163], v[218:221], v[64:67]
	s_setprio 0
	s_setprio 1
	v_mfma_f32_16x16x32_bf16 v[28:31], v[174:177], v[190:193], v[28:31]
	v_mfma_f32_16x16x32_bf16 v[24:27], v[182:185], v[190:193], v[24:27]
	v_mfma_f32_16x16x32_bf16 v[20:23], v[174:177], v[198:201], v[20:23]
	v_mfma_f32_16x16x32_bf16 v[16:19], v[182:185], v[198:201], v[16:19]
	v_mfma_f32_16x16x32_bf16 v[12:15], v[174:177], v[206:209], v[12:15]
	v_mfma_f32_16x16x32_bf16 v[8:11], v[182:185], v[206:209], v[8:11]
	v_mfma_f32_16x16x32_bf16 v[4:7], v[174:177], v[214:217], v[4:7]
	v_mfma_f32_16x16x32_bf16 v[0:3], v[182:185], v[214:217], v[0:3]
	v_mfma_f32_16x16x32_bf16 v[28:31], v[178:181], v[194:197], v[28:31]
	v_mfma_f32_16x16x32_bf16 v[24:27], v[186:189], v[194:197], v[24:27]
	v_mfma_f32_16x16x32_bf16 v[20:23], v[178:181], v[202:205], v[20:23]
	v_mfma_f32_16x16x32_bf16 v[16:19], v[186:189], v[202:205], v[16:19]
	v_mfma_f32_16x16x32_bf16 v[12:15], v[178:181], v[210:213], v[12:15]
	v_mfma_f32_16x16x32_bf16 v[8:11], v[186:189], v[210:213], v[8:11]
	v_mfma_f32_16x16x32_bf16 v[4:7], v[178:181], v[218:221], v[4:7]
	v_mfma_f32_16x16x32_bf16 v[0:3], v[186:189], v[218:221], v[0:3]
	s_setprio 0
	s_barrier
	s_add_i32 s35, 0, 0x18000
	v_add_u32_e32 v136, s35, v165
	s_add_i32 s57, 0, 0x1c000
	ds_read_b128 v[148:151], v136
	ds_read_b128 v[152:155], v136 offset:1024
	ds_read_b128 v[156:159], v136 offset:2048
	ds_read_b128 v[160:163], v136 offset:3072
	v_add_u32_e32 v136, s57, v165
	ds_read_b128 v[174:177], v136
	ds_read_b128 v[178:181], v136 offset:1024
	ds_read_b128 v[182:185], v136 offset:2048
	ds_read_b128 v[186:189], v136 offset:3072
	s_add_u32 s28, s28, 0x100000
	s_addc_u32 s29, s29, 0
	s_mov_b32 m0, s43
	v_lshl_add_u64 v[190:191], s[28:29], 0, v[128:129]
	global_load_lds_dwordx4 v[190:191], off
	v_lshl_add_u64 v[190:191], s[28:29], 0, v[132:133]
	s_mov_b32 m0, s44
	s_nop 0
	global_load_lds_dwordx4 v[190:191], off
	ds_read_b128 v[190:193], v171 offset:32768
	ds_read_b128 v[194:197], v171 offset:33792
	ds_read_b128 v[198:201], v171 offset:34816
	ds_read_b128 v[202:205], v171 offset:35840
	ds_read_b128 v[206:209], v171 offset:36864
	ds_read_b128 v[210:213], v171 offset:37888
	ds_read_b128 v[214:217], v171 offset:38912
	ds_read_b128 v[218:221], v171 offset:39936
	s_waitcnt vmcnt(8)
	s_waitcnt lgkmcnt(0)
	s_barrier
	s_setprio 1
	s_waitcnt lgkmcnt(0)
	v_mfma_f32_16x16x32_bf16 v[124:127], v[148:151], v[190:193], v[124:127]
	v_mfma_f32_16x16x32_bf16 v[120:123], v[156:159], v[190:193], v[120:123]
	v_mfma_f32_16x16x32_bf16 v[116:119], v[148:151], v[198:201], v[116:119]
	v_mfma_f32_16x16x32_bf16 v[112:115], v[156:159], v[198:201], v[112:115]
	v_mfma_f32_16x16x32_bf16 v[108:111], v[148:151], v[206:209], v[108:111]
	v_mfma_f32_16x16x32_bf16 v[104:107], v[156:159], v[206:209], v[104:107]
	v_mfma_f32_16x16x32_bf16 v[100:103], v[148:151], v[214:217], v[100:103]
	v_mfma_f32_16x16x32_bf16 v[96:99], v[156:159], v[214:217], v[96:99]
	v_mfma_f32_16x16x32_bf16 v[124:127], v[152:155], v[194:197], v[124:127]
	v_mfma_f32_16x16x32_bf16 v[120:123], v[160:163], v[194:197], v[120:123]
	v_mfma_f32_16x16x32_bf16 v[116:119], v[152:155], v[202:205], v[116:119]
	v_mfma_f32_16x16x32_bf16 v[112:115], v[160:163], v[202:205], v[112:115]
	v_mfma_f32_16x16x32_bf16 v[108:111], v[152:155], v[210:213], v[108:111]
	v_mfma_f32_16x16x32_bf16 v[104:107], v[160:163], v[210:213], v[104:107]
	v_mfma_f32_16x16x32_bf16 v[100:103], v[152:155], v[218:221], v[100:103]
	v_mfma_f32_16x16x32_bf16 v[96:99], v[160:163], v[218:221], v[96:99]
	s_setprio 0
	s_setprio 1
	v_mfma_f32_16x16x32_bf16 v[60:63], v[174:177], v[190:193], v[60:63]
	v_mfma_f32_16x16x32_bf16 v[56:59], v[182:185], v[190:193], v[56:59]
	v_mfma_f32_16x16x32_bf16 v[52:55], v[174:177], v[198:201], v[52:55]
	v_mfma_f32_16x16x32_bf16 v[48:51], v[182:185], v[198:201], v[48:51]
	v_mfma_f32_16x16x32_bf16 v[44:47], v[174:177], v[206:209], v[44:47]
	v_mfma_f32_16x16x32_bf16 v[40:43], v[182:185], v[206:209], v[40:43]
	v_mfma_f32_16x16x32_bf16 v[36:39], v[174:177], v[214:217], v[36:39]
	v_mfma_f32_16x16x32_bf16 v[32:35], v[182:185], v[214:217], v[32:35]
	v_mfma_f32_16x16x32_bf16 v[60:63], v[178:181], v[194:197], v[60:63]
	v_mfma_f32_16x16x32_bf16 v[56:59], v[186:189], v[194:197], v[56:59]
	v_mfma_f32_16x16x32_bf16 v[52:55], v[178:181], v[202:205], v[52:55]
	v_mfma_f32_16x16x32_bf16 v[48:51], v[186:189], v[202:205], v[48:51]
	v_mfma_f32_16x16x32_bf16 v[44:47], v[178:181], v[210:213], v[44:47]
	v_mfma_f32_16x16x32_bf16 v[40:43], v[186:189], v[210:213], v[40:43]
	v_mfma_f32_16x16x32_bf16 v[36:39], v[178:181], v[218:221], v[36:39]
	v_mfma_f32_16x16x32_bf16 v[32:35], v[186:189], v[218:221], v[32:35]
	s_setprio 0
	s_barrier
	s_add_i32 s28, s35, s36
	v_lshl_add_u64 v[190:191], v[222:223], 0, s[12:13]
	s_mov_b32 m0, s28
	s_nop 0
	global_load_lds_dwordx4 v[190:191], off
	s_add_i32 m0, s28, 0x2000
	s_add_u32 s26, s26, 0x100800
	v_lshl_add_u64 v[190:191], v[224:225], 0, s[12:13]
	s_addc_u32 s27, s27, 0
	s_add_i32 s28, s57, s36
	global_load_lds_dwordx4 v[190:191], off
	v_lshl_add_u64 v[190:191], s[26:27], 0, v[130:131]
	s_mov_b32 m0, s28
	s_nop 0
	global_load_lds_dwordx4 v[190:191], off
	v_lshl_add_u64 v[190:191], s[26:27], 0, v[134:135]
	s_add_i32 m0, s28, 0x2000
	s_nop 0
	global_load_lds_dwordx4 v[190:191], off
	v_lshl_add_u64 v[190:191], v[226:227], 0, s[12:13]
	s_mov_b32 m0, s49
	s_nop 0
	global_load_lds_dwordx4 v[190:191], off
	v_lshl_add_u64 v[190:191], v[228:229], 0, s[12:13]
	s_mov_b32 m0, s50
	s_nop 0
	global_load_lds_dwordx4 v[190:191], off
	ds_read_b128 v[190:193], v171 offset:49152
	ds_read_b128 v[194:197], v171 offset:50176
	ds_read_b128 v[198:201], v171 offset:51200
	ds_read_b128 v[202:205], v171 offset:52224
	ds_read_b128 v[206:209], v171 offset:53248
	ds_read_b128 v[210:213], v171 offset:54272
	ds_read_b128 v[214:217], v171 offset:55296
	ds_read_b128 v[218:221], v171 offset:56320
	s_waitcnt vmcnt(8)
	s_waitcnt lgkmcnt(0)
	s_barrier
	s_setprio 1
	s_waitcnt lgkmcnt(0)
	v_mfma_f32_16x16x32_bf16 v[92:95], v[148:151], v[190:193], v[92:95]
	v_mfma_f32_16x16x32_bf16 v[88:91], v[156:159], v[190:193], v[88:91]
	v_mfma_f32_16x16x32_bf16 v[84:87], v[148:151], v[198:201], v[84:87]
	v_mfma_f32_16x16x32_bf16 v[80:83], v[156:159], v[198:201], v[80:83]
	v_mfma_f32_16x16x32_bf16 v[76:79], v[148:151], v[206:209], v[76:79]
	v_mfma_f32_16x16x32_bf16 v[72:75], v[156:159], v[206:209], v[72:75]
	v_mfma_f32_16x16x32_bf16 v[68:71], v[148:151], v[214:217], v[68:71]
	v_mfma_f32_16x16x32_bf16 v[64:67], v[156:159], v[214:217], v[64:67]
	v_mfma_f32_16x16x32_bf16 v[92:95], v[152:155], v[194:197], v[92:95]
	v_mfma_f32_16x16x32_bf16 v[88:91], v[160:163], v[194:197], v[88:91]
	v_mfma_f32_16x16x32_bf16 v[84:87], v[152:155], v[202:205], v[84:87]
	v_mfma_f32_16x16x32_bf16 v[80:83], v[160:163], v[202:205], v[80:83]
	v_mfma_f32_16x16x32_bf16 v[76:79], v[152:155], v[210:213], v[76:79]
	v_mfma_f32_16x16x32_bf16 v[72:75], v[160:163], v[210:213], v[72:75]
	v_mfma_f32_16x16x32_bf16 v[68:71], v[152:155], v[218:221], v[68:71]
	v_mfma_f32_16x16x32_bf16 v[64:67], v[160:163], v[218:221], v[64:67]
	s_setprio 0
	s_setprio 1
	v_mfma_f32_16x16x32_bf16 v[28:31], v[174:177], v[190:193], v[28:31]
	v_mfma_f32_16x16x32_bf16 v[24:27], v[182:185], v[190:193], v[24:27]
	v_mfma_f32_16x16x32_bf16 v[20:23], v[174:177], v[198:201], v[20:23]
	v_mfma_f32_16x16x32_bf16 v[16:19], v[182:185], v[198:201], v[16:19]
	v_mfma_f32_16x16x32_bf16 v[12:15], v[174:177], v[206:209], v[12:15]
	v_mfma_f32_16x16x32_bf16 v[8:11], v[182:185], v[206:209], v[8:11]
	v_mfma_f32_16x16x32_bf16 v[4:7], v[174:177], v[214:217], v[4:7]
	v_mfma_f32_16x16x32_bf16 v[0:3], v[182:185], v[214:217], v[0:3]
	v_mfma_f32_16x16x32_bf16 v[28:31], v[178:181], v[194:197], v[28:31]
	v_mfma_f32_16x16x32_bf16 v[24:27], v[186:189], v[194:197], v[24:27]
	v_mfma_f32_16x16x32_bf16 v[20:23], v[178:181], v[202:205], v[20:23]
	v_mfma_f32_16x16x32_bf16 v[16:19], v[186:189], v[202:205], v[16:19]
	v_mfma_f32_16x16x32_bf16 v[12:15], v[178:181], v[210:213], v[12:15]
	v_mfma_f32_16x16x32_bf16 v[8:11], v[186:189], v[210:213], v[8:11]
	v_mfma_f32_16x16x32_bf16 v[4:7], v[178:181], v[218:221], v[4:7]
	v_mfma_f32_16x16x32_bf16 v[0:3], v[186:189], v[218:221], v[0:3]
	s_setprio 0
	s_barrier
	s_add_i32 s34, s34, 2
	s_add_u32 s6, s6, 0x1000
	s_addc_u32 s7, s7, 0
	s_add_u32 s30, s30, 0x1000
	s_addc_u32 s31, s31, 0
	s_cmp_gt_u32 s34, 61
	s_cbranch_scc0 .LBB0_200
	s_and_b64 vcc, exec, s[0:1]
	s_cbranch_vccz .LBB0_203
	s_barrier

.LBB0_333:
	ds_read_b128 v[144:147], v152
	ds_read_b128 v[156:159], v152 offset:1024
	ds_read_b128 v[160:163], v152 offset:2048
	ds_read_b128 v[164:167], v152 offset:3072
	ds_read_b128 v[168:171], v153
	ds_read_b128 v[172:175], v153 offset:1024
	ds_read_b128 v[176:179], v153 offset:2048
	ds_read_b128 v[180:183], v153 offset:3072
	s_add_u32 s28, s24, 0x100
	s_addc_u32 s29, s25, 0
	s_cmp_eq_u32 s56, 60
	s_cselect_b32 s35, s13, s29
	s_cselect_b32 s34, s52, s28
	s_cselect_b32 s31, s11, s55
	s_cselect_b32 s30, s53, s54
	v_lshl_add_u64 v[184:185], s[24:25], 0, v[136:137]
	s_add_i32 m0, s21, 0xc000
	s_nop 0
	global_load_lds_dwordx4 v[184:185], off
	v_lshl_add_u64 v[184:185], s[24:25], 0, v[138:139]
	s_add_i32 m0, s21, 0xe000
	s_nop 0
	global_load_lds_dwordx4 v[184:185], off
	ds_read_b128 v[184:187], v154
	ds_read_b128 v[188:191], v154 offset:1024
	ds_read_b128 v[192:195], v154 offset:2048
	ds_read_b128 v[196:199], v154 offset:3072
	ds_read_b128 v[200:203], v154 offset:4096
	ds_read_b128 v[204:207], v154 offset:5120
	ds_read_b128 v[208:211], v154 offset:6144
	ds_read_b128 v[212:215], v154 offset:7168
	s_waitcnt vmcnt(8)
	s_waitcnt lgkmcnt(0)
	s_barrier
	s_setprio 1
	s_waitcnt lgkmcnt(0)
	v_mfma_f32_16x16x32_bf16 v[124:127], v[144:147], v[184:187], v[124:127]
	v_mfma_f32_16x16x32_bf16 v[120:123], v[160:163], v[184:187], v[120:123]
	v_mfma_f32_16x16x32_bf16 v[116:119], v[144:147], v[192:195], v[116:119]
	v_mfma_f32_16x16x32_bf16 v[108:111], v[160:163], v[192:195], v[108:111]
	v_mfma_f32_16x16x32_bf16 v[100:103], v[144:147], v[200:203], v[100:103]
	v_mfma_f32_16x16x32_bf16 v[92:95], v[160:163], v[200:203], v[92:95]
	v_mfma_f32_16x16x32_bf16 v[84:87], v[144:147], v[208:211], v[84:87]
	v_mfma_f32_16x16x32_bf16 v[76:79], v[160:163], v[208:211], v[76:79]
	v_mfma_f32_16x16x32_bf16 v[124:127], v[156:159], v[188:191], v[124:127]
	v_mfma_f32_16x16x32_bf16 v[120:123], v[164:167], v[188:191], v[120:123]
	v_mfma_f32_16x16x32_bf16 v[116:119], v[156:159], v[196:199], v[116:119]
	v_mfma_f32_16x16x32_bf16 v[108:111], v[164:167], v[196:199], v[108:111]
	v_mfma_f32_16x16x32_bf16 v[100:103], v[156:159], v[204:207], v[100:103]
	v_mfma_f32_16x16x32_bf16 v[92:95], v[164:167], v[204:207], v[92:95]
	v_mfma_f32_16x16x32_bf16 v[84:87], v[156:159], v[212:215], v[84:87]
	v_mfma_f32_16x16x32_bf16 v[76:79], v[164:167], v[212:215], v[76:79]
	s_setprio 0
	s_setprio 1
	v_mfma_f32_16x16x32_bf16 v[112:115], v[168:171], v[184:187], v[112:115]
	v_mfma_f32_16x16x32_bf16 v[104:107], v[176:179], v[184:187], v[104:107]
	v_mfma_f32_16x16x32_bf16 v[96:99], v[168:171], v[192:195], v[96:99]
	v_mfma_f32_16x16x32_bf16 v[88:91], v[176:179], v[192:195], v[88:91]
	v_mfma_f32_16x16x32_bf16 v[80:83], v[168:171], v[200:203], v[80:83]
	v_mfma_f32_16x16x32_bf16 v[72:75], v[176:179], v[200:203], v[72:75]
	v_mfma_f32_16x16x32_bf16 v[68:71], v[168:171], v[208:211], v[68:71]
	v_mfma_f32_16x16x32_bf16 v[64:67], v[176:179], v[208:211], v[64:67]
	v_mfma_f32_16x16x32_bf16 v[112:115], v[172:175], v[188:191], v[112:115]
	v_mfma_f32_16x16x32_bf16 v[104:107], v[180:183], v[188:191], v[104:107]
	v_mfma_f32_16x16x32_bf16 v[96:99], v[172:175], v[196:199], v[96:99]
	v_mfma_f32_16x16x32_bf16 v[88:91], v[180:183], v[196:199], v[88:91]
	v_mfma_f32_16x16x32_bf16 v[80:83], v[172:175], v[204:207], v[80:83]
	v_mfma_f32_16x16x32_bf16 v[72:75], v[180:183], v[204:207], v[72:75]
	v_mfma_f32_16x16x32_bf16 v[68:71], v[172:175], v[212:215], v[68:71]
	v_mfma_f32_16x16x32_bf16 v[64:67], v[180:183], v[212:215], v[64:67]
	s_setprio 0
	s_barrier
	s_add_i32 s24, s49, s41
	v_lshl_add_u64 v[216:217], s[30:31], 0, v[130:131]
	s_mov_b32 m0, s24
	v_lshl_add_u64 v[218:219], s[30:31], 0, v[134:135]
	global_load_lds_dwordx4 v[216:217], off
	s_add_i32 m0, s24, 0x2000
	s_add_u32 s24, s30, 0x100000
	s_addc_u32 s25, s31, 0
	s_add_i32 s57, s50, s41
	global_load_lds_dwordx4 v[218:219], off
	v_lshl_add_u64 v[184:185], s[24:25], 0, v[130:131]
	s_mov_b32 m0, s57
	v_lshl_add_u64 v[220:221], s[34:35], 0, v[128:129]
	global_load_lds_dwordx4 v[184:185], off
	v_lshl_add_u64 v[184:185], s[24:25], 0, v[134:135]
	s_add_i32 m0, s57, 0x2000
	v_lshl_add_u64 v[222:223], s[34:35], 0, v[132:133]
	global_load_lds_dwordx4 v[184:185], off
	s_mov_b32 m0, s21
	s_nop 0
	global_load_lds_dwordx4 v[220:221], off
	s_mov_b32 m0, s42
	s_nop 0
	global_load_lds_dwordx4 v[222:223], off
	ds_read_b128 v[184:187], v154 offset:16384
	ds_read_b128 v[188:191], v154 offset:17408
	ds_read_b128 v[192:195], v154 offset:18432
	ds_read_b128 v[196:199], v154 offset:19456
	ds_read_b128 v[200:203], v154 offset:20480
	ds_read_b128 v[204:207], v154 offset:21504
	ds_read_b128 v[208:211], v154 offset:22528
	ds_read_b128 v[212:215], v154 offset:23552
	s_waitcnt vmcnt(8)
	s_waitcnt lgkmcnt(0)
	s_barrier
	s_setprio 1
	s_waitcnt lgkmcnt(0)
	v_mfma_f32_16x16x32_bf16 v[60:63], v[144:147], v[184:187], v[60:63]
	v_mfma_f32_16x16x32_bf16 v[56:59], v[160:163], v[184:187], v[56:59]
	v_mfma_f32_16x16x32_bf16 v[52:55], v[144:147], v[192:195], v[52:55]
	v_mfma_f32_16x16x32_bf16 v[44:47], v[160:163], v[192:195], v[44:47]
	v_mfma_f32_16x16x32_bf16 v[36:39], v[144:147], v[200:203], v[36:39]
	v_mfma_f32_16x16x32_bf16 v[28:31], v[160:163], v[200:203], v[28:31]
	v_mfma_f32_16x16x32_bf16 v[20:23], v[144:147], v[208:211], v[20:23]
	v_mfma_f32_16x16x32_bf16 v[12:15], v[160:163], v[208:211], v[12:15]
	v_mfma_f32_16x16x32_bf16 v[60:63], v[156:159], v[188:191], v[60:63]
	v_mfma_f32_16x16x32_bf16 v[56:59], v[164:167], v[188:191], v[56:59]
	v_mfma_f32_16x16x32_bf16 v[52:55], v[156:159], v[196:199], v[52:55]
	v_mfma_f32_16x16x32_bf16 v[44:47], v[164:167], v[196:199], v[44:47]
	v_mfma_f32_16x16x32_bf16 v[36:39], v[156:159], v[204:207], v[36:39]
	v_mfma_f32_16x16x32_bf16 v[28:31], v[164:167], v[204:207], v[28:31]
	v_mfma_f32_16x16x32_bf16 v[20:23], v[156:159], v[212:215], v[20:23]
	v_mfma_f32_16x16x32_bf16 v[12:15], v[164:167], v[212:215], v[12:15]
	s_setprio 0
	s_setprio 1
	v_mfma_f32_16x16x32_bf16 v[48:51], v[168:171], v[184:187], v[48:51]
	v_mfma_f32_16x16x32_bf16 v[40:43], v[176:179], v[184:187], v[40:43]
	v_mfma_f32_16x16x32_bf16 v[32:35], v[168:171], v[192:195], v[32:35]
	v_mfma_f32_16x16x32_bf16 v[24:27], v[176:179], v[192:195], v[24:27]
	v_mfma_f32_16x16x32_bf16 v[16:19], v[168:171], v[200:203], v[16:19]
	v_mfma_f32_16x16x32_bf16 v[8:11], v[176:179], v[200:203], v[8:11]
	v_mfma_f32_16x16x32_bf16 v[4:7], v[168:171], v[208:211], v[4:7]
	v_mfma_f32_16x16x32_bf16 v[0:3], v[176:179], v[208:211], v[0:3]
	v_mfma_f32_16x16x32_bf16 v[48:51], v[172:175], v[188:191], v[48:51]
	v_mfma_f32_16x16x32_bf16 v[40:43], v[180:183], v[188:191], v[40:43]
	v_mfma_f32_16x16x32_bf16 v[32:35], v[172:175], v[196:199], v[32:35]
	v_mfma_f32_16x16x32_bf16 v[24:27], v[180:183], v[196:199], v[24:27]
	v_mfma_f32_16x16x32_bf16 v[16:19], v[172:175], v[204:207], v[16:19]
	v_mfma_f32_16x16x32_bf16 v[8:11], v[180:183], v[204:207], v[8:11]
	v_mfma_f32_16x16x32_bf16 v[4:7], v[172:175], v[212:215], v[4:7]
	v_mfma_f32_16x16x32_bf16 v[0:3], v[180:183], v[212:215], v[0:3]
	s_setprio 0
	s_barrier
	s_add_i32 s57, 0, 0x18000
	v_add_u32_e32 v155, s57, v149
	s_add_i32 s58, 0, 0x1c000
	ds_read_b128 v[144:147], v155
	ds_read_b128 v[156:159], v155 offset:1024
	ds_read_b128 v[160:163], v155 offset:2048
	ds_read_b128 v[164:167], v155 offset:3072
	v_add_u32_e32 v155, s58, v149
	ds_read_b128 v[168:171], v155
	ds_read_b128 v[172:175], v155 offset:1024
	ds_read_b128 v[176:179], v155 offset:2048
	ds_read_b128 v[180:183], v155 offset:3072
	s_add_u32 s24, s34, 0x100000
	s_addc_u32 s25, s35, 0
	s_mov_b32 m0, s43
	v_lshl_add_u64 v[184:185], s[24:25], 0, v[128:129]
	global_load_lds_dwordx4 v[184:185], off
	v_lshl_add_u64 v[184:185], s[24:25], 0, v[132:133]
	s_mov_b32 m0, s44
	s_nop 0
	global_load_lds_dwordx4 v[184:185], off
	ds_read_b128 v[184:187], v154 offset:32768
	ds_read_b128 v[188:191], v154 offset:33792
	ds_read_b128 v[192:195], v154 offset:34816
	ds_read_b128 v[196:199], v154 offset:35840
	ds_read_b128 v[200:203], v154 offset:36864
	ds_read_b128 v[204:207], v154 offset:37888
	ds_read_b128 v[208:211], v154 offset:38912
	ds_read_b128 v[212:215], v154 offset:39936
	s_waitcnt vmcnt(8)
	s_waitcnt lgkmcnt(0)
	s_barrier
	s_setprio 1
	s_waitcnt lgkmcnt(0)
	v_mfma_f32_16x16x32_bf16 v[124:127], v[144:147], v[184:187], v[124:127]
	v_mfma_f32_16x16x32_bf16 v[120:123], v[160:163], v[184:187], v[120:123]
	v_mfma_f32_16x16x32_bf16 v[116:119], v[144:147], v[192:195], v[116:119]
	v_mfma_f32_16x16x32_bf16 v[108:111], v[160:163], v[192:195], v[108:111]
	v_mfma_f32_16x16x32_bf16 v[100:103], v[144:147], v[200:203], v[100:103]
	v_mfma_f32_16x16x32_bf16 v[92:95], v[160:163], v[200:203], v[92:95]
	v_mfma_f32_16x16x32_bf16 v[84:87], v[144:147], v[208:211], v[84:87]
	v_mfma_f32_16x16x32_bf16 v[76:79], v[160:163], v[208:211], v[76:79]
	v_mfma_f32_16x16x32_bf16 v[124:127], v[156:159], v[188:191], v[124:127]
	v_mfma_f32_16x16x32_bf16 v[120:123], v[164:167], v[188:191], v[120:123]
	v_mfma_f32_16x16x32_bf16 v[116:119], v[156:159], v[196:199], v[116:119]
	v_mfma_f32_16x16x32_bf16 v[108:111], v[164:167], v[196:199], v[108:111]
	v_mfma_f32_16x16x32_bf16 v[100:103], v[156:159], v[204:207], v[100:103]
	v_mfma_f32_16x16x32_bf16 v[92:95], v[164:167], v[204:207], v[92:95]
	v_mfma_f32_16x16x32_bf16 v[84:87], v[156:159], v[212:215], v[84:87]
	v_mfma_f32_16x16x32_bf16 v[76:79], v[164:167], v[212:215], v[76:79]
	s_setprio 0
	s_setprio 1
	v_mfma_f32_16x16x32_bf16 v[112:115], v[168:171], v[184:187], v[112:115]
	v_mfma_f32_16x16x32_bf16 v[104:107], v[176:179], v[184:187], v[104:107]
	v_mfma_f32_16x16x32_bf16 v[96:99], v[168:171], v[192:195], v[96:99]
	v_mfma_f32_16x16x32_bf16 v[88:91], v[176:179], v[192:195], v[88:91]
	v_mfma_f32_16x16x32_bf16 v[80:83], v[168:171], v[200:203], v[80:83]
	v_mfma_f32_16x16x32_bf16 v[72:75], v[176:179], v[200:203], v[72:75]
	v_mfma_f32_16x16x32_bf16 v[68:71], v[168:171], v[208:211], v[68:71]
	v_mfma_f32_16x16x32_bf16 v[64:67], v[176:179], v[208:211], v[64:67]
	v_mfma_f32_16x16x32_bf16 v[112:115], v[172:175], v[188:191], v[112:115]
	v_mfma_f32_16x16x32_bf16 v[104:107], v[180:183], v[188:191], v[104:107]
	v_mfma_f32_16x16x32_bf16 v[96:99], v[172:175], v[196:199], v[96:99]
	v_mfma_f32_16x16x32_bf16 v[88:91], v[180:183], v[196:199], v[88:91]
	v_mfma_f32_16x16x32_bf16 v[80:83], v[172:175], v[204:207], v[80:83]
	v_mfma_f32_16x16x32_bf16 v[72:75], v[180:183], v[204:207], v[72:75]
	v_mfma_f32_16x16x32_bf16 v[68:71], v[172:175], v[212:215], v[68:71]
	v_mfma_f32_16x16x32_bf16 v[64:67], v[180:183], v[212:215], v[64:67]
	s_setprio 0
	s_barrier
	s_add_i32 s24, s57, s41
	v_lshl_add_u64 v[184:185], v[216:217], 0, s[8:9]
	s_mov_b32 m0, s24
	s_nop 0
	global_load_lds_dwordx4 v[184:185], off
	s_add_i32 m0, s24, 0x2000
	s_add_u32 s24, s30, 0x100080
	v_lshl_add_u64 v[184:185], v[218:219], 0, s[8:9]
	s_addc_u32 s25, s31, 0
	s_add_i32 s30, s58, s41
	global_load_lds_dwordx4 v[184:185], off
	v_lshl_add_u64 v[184:185], s[24:25], 0, v[130:131]
	s_mov_b32 m0, s30
	s_nop 0
	global_load_lds_dwordx4 v[184:185], off
	v_lshl_add_u64 v[184:185], s[24:25], 0, v[134:135]
	s_add_i32 m0, s30, 0x2000
	s_nop 0
	global_load_lds_dwordx4 v[184:185], off
	v_lshl_add_u64 v[184:185], v[220:221], 0, s[8:9]
	s_mov_b32 m0, s46
	s_nop 0
	global_load_lds_dwordx4 v[184:185], off
	v_lshl_add_u64 v[184:185], v[222:223], 0, s[8:9]
	s_mov_b32 m0, s47
	s_nop 0
	global_load_lds_dwordx4 v[184:185], off
	ds_read_b128 v[184:187], v154 offset:49152
	ds_read_b128 v[188:191], v154 offset:50176
	ds_read_b128 v[192:195], v154 offset:51200
	ds_read_b128 v[196:199], v154 offset:52224
	ds_read_b128 v[200:203], v154 offset:53248
	ds_read_b128 v[204:207], v154 offset:54272
	ds_read_b128 v[208:211], v154 offset:55296
	ds_read_b128 v[212:215], v154 offset:56320
	s_waitcnt vmcnt(8)
	s_waitcnt lgkmcnt(0)
	s_barrier
	s_setprio 1
	s_waitcnt lgkmcnt(0)
	v_mfma_f32_16x16x32_bf16 v[60:63], v[144:147], v[184:187], v[60:63]
	v_mfma_f32_16x16x32_bf16 v[56:59], v[160:163], v[184:187], v[56:59]
	v_mfma_f32_16x16x32_bf16 v[52:55], v[144:147], v[192:195], v[52:55]
	v_mfma_f32_16x16x32_bf16 v[44:47], v[160:163], v[192:195], v[44:47]
	v_mfma_f32_16x16x32_bf16 v[36:39], v[144:147], v[200:203], v[36:39]
	v_mfma_f32_16x16x32_bf16 v[28:31], v[160:163], v[200:203], v[28:31]
	v_mfma_f32_16x16x32_bf16 v[20:23], v[144:147], v[208:211], v[20:23]
	v_mfma_f32_16x16x32_bf16 v[12:15], v[160:163], v[208:211], v[12:15]
	v_mfma_f32_16x16x32_bf16 v[60:63], v[156:159], v[188:191], v[60:63]
	v_mfma_f32_16x16x32_bf16 v[56:59], v[164:167], v[188:191], v[56:59]
	v_mfma_f32_16x16x32_bf16 v[52:55], v[156:159], v[196:199], v[52:55]
	v_mfma_f32_16x16x32_bf16 v[44:47], v[164:167], v[196:199], v[44:47]
	v_mfma_f32_16x16x32_bf16 v[36:39], v[156:159], v[204:207], v[36:39]
	v_mfma_f32_16x16x32_bf16 v[28:31], v[164:167], v[204:207], v[28:31]
	v_mfma_f32_16x16x32_bf16 v[20:23], v[156:159], v[212:215], v[20:23]
	v_mfma_f32_16x16x32_bf16 v[12:15], v[164:167], v[212:215], v[12:15]
	s_setprio 0
	s_setprio 1
	v_mfma_f32_16x16x32_bf16 v[48:51], v[168:171], v[184:187], v[48:51]
	v_mfma_f32_16x16x32_bf16 v[40:43], v[176:179], v[184:187], v[40:43]
	v_mfma_f32_16x16x32_bf16 v[32:35], v[168:171], v[192:195], v[32:35]
	v_mfma_f32_16x16x32_bf16 v[24:27], v[176:179], v[192:195], v[24:27]
	v_mfma_f32_16x16x32_bf16 v[16:19], v[168:171], v[200:203], v[16:19]
	v_mfma_f32_16x16x32_bf16 v[8:11], v[176:179], v[200:203], v[8:11]
	v_mfma_f32_16x16x32_bf16 v[4:7], v[168:171], v[208:211], v[4:7]
	v_mfma_f32_16x16x32_bf16 v[0:3], v[176:179], v[208:211], v[0:3]
	v_mfma_f32_16x16x32_bf16 v[48:51], v[172:175], v[188:191], v[48:51]
	v_mfma_f32_16x16x32_bf16 v[40:43], v[180:183], v[188:191], v[40:43]
	v_mfma_f32_16x16x32_bf16 v[32:35], v[172:175], v[196:199], v[32:35]
	v_mfma_f32_16x16x32_bf16 v[24:27], v[180:183], v[196:199], v[24:27]
	v_mfma_f32_16x16x32_bf16 v[16:19], v[172:175], v[204:207], v[16:19]
	v_mfma_f32_16x16x32_bf16 v[8:11], v[180:183], v[204:207], v[8:11]
	v_mfma_f32_16x16x32_bf16 v[4:7], v[172:175], v[212:215], v[4:7]
	v_mfma_f32_16x16x32_bf16 v[0:3], v[180:183], v[212:215], v[0:3]
	s_setprio 0
	s_barrier
	s_add_i32 s56, s56, 2
	s_add_u32 s54, s54, 0x100
	s_addc_u32 s55, s55, 0
	s_cmp_gt_u32 s56, 61
	s_mov_b64 s[24:25], s[28:29]
	s_cbranch_scc0 .LBB0_333
	s_and_b64 vcc, exec, s[0:1]
	s_cbranch_vccz .LBB0_336
	s_barrier

.LBB0_799:
	v_readfirstlane_b32 s6, v222
	s_add_i32 s80, s88, s6
	v_add_f32_e32 v222, v130, v131
	s_add_i32 s7, s77, -1
	v_fmac_f32_e32 v222, v223, v224
	s_cmp_ge_u32 s7, s86
	s_waitcnt lgkmcnt(0)
	s_barrier
	s_cbranch_scc1 .LBB0_831
	s_cmp_lt_i32 s80, s81
	s_cselect_b64 s[8:9], -1, 0
	s_mov_b64 s[6:7], -1
	s_and_b64 vcc, exec, s[94:95]
	v_cndmask_b32_e64 v223, 0, 1, s[8:9]
	s_cbranch_vccz .LBB0_804
	s_andn2_b64 vcc, exec, s[8:9]
	s_cbranch_vccnz .LBB0_803
	s_ashr_i32 s7, s80, 31
	s_ashr_i32 s6, s80, 1
	s_lshr_b32 s7, s7, 26
	s_add_i32 s7, s6, s7
	s_andn2_b32 s7, s7, 63
	s_sub_i32 s10, s6, s7
	s_lshl_b32 s6, s80, 5
	s_and_b32 s6, s6, 32
	s_or_b32 s6, s6, s97
	s_or_b32 s6, s6, s7
	s_ashr_i32 s7, s6, 31
	s_lshl_b64 s[6:7], s[6:7], 14
	s_add_u32 s11, s70, s6
	s_addc_u32 s12, s71, s7
	s_lshl_b32 s6, s10, 6
	s_ashr_i32 s7, s6, 31
	s_lshl_b64 s[6:7], s[6:7], 2
	s_add_u32 s6, s11, s6
	s_mul_hi_i32 s10, s80, 0x55555556
	s_addc_u32 s7, s12, s7
	s_lshr_b32 s11, s10, 31
	s_add_i32 s10, s10, s11
	s_mul_i32 s10, s10, 3
	s_sub_i32 s10, s80, s10
	s_lshl_b32 s10, s10, 13
	s_add_i32 s10, s73, s10
	v_lshl_add_u64 v[130:131], s[6:7], 0, v[0:1]
	s_mov_b32 m0, s10
	s_mov_b64 s[6:7], 0x10000
	global_load_lds_dwordx4 v[130:131], off
	v_lshl_add_u64 v[130:131], v[130:131], 0, s[6:7]
	s_add_i32 m0, s10, 0x400
	s_nop 0
	global_load_lds_dwordx4 v[130:131], off

.LBB0_838:
	s_and_b64 s[0:1], s[74:75], exec
	v_add_f32_e32 v130, v130, v131
	s_cselect_b32 s0, 6, 0
	v_readfirstlane_b32 s1, v223
	v_fmac_f32_e32 v130, v222, v224
	s_or_b32 s87, s0, s1
	s_add_i32 s80, s80, s1
	v_mov_b32_e32 v222, v130
	s_waitcnt lgkmcnt(0)
	s_barrier

.LBB0_1202:
	ds_read_b128 v[128:131], v176
	ds_read_b128 v[132:135], v176 offset:1024
	ds_read_b128 v[136:139], v176 offset:2048
	ds_read_b128 v[140:143], v176 offset:3072
	ds_read_b128 v[144:147], v177
	ds_read_b128 v[148:151], v177 offset:1024
	ds_read_b128 v[180:183], v177 offset:2048
	ds_read_b128 v[184:187], v177 offset:3072
	s_add_u32 s30, s28, 0xfff00080
	s_addc_u32 s31, s29, -1
	s_cmp_eq_u32 s40, 60
	s_cselect_b32 s35, s23, s31
	s_cselect_b32 s34, s36, s30
	s_cselect_b32 s31, s21, s39
	s_cselect_b32 s30, s37, s38
	v_lshl_add_u64 v[172:173], s[28:29], 0, v[164:165]
	s_add_i32 m0, s7, 0xc000
	s_nop 0
	global_load_lds_dwordx4 v[172:173], off
	v_lshl_add_u64 v[172:173], s[28:29], 0, v[166:167]
	s_add_i32 m0, s7, 0xe000
	s_nop 0
	global_load_lds_dwordx4 v[172:173], off
	ds_read_b128 v[188:191], v178
	ds_read_b128 v[192:195], v178 offset:1024
	ds_read_b128 v[196:199], v178 offset:2048
	ds_read_b128 v[200:203], v178 offset:3072
	ds_read_b128 v[204:207], v178 offset:4096
	ds_read_b128 v[208:211], v178 offset:5120
	ds_read_b128 v[212:215], v178 offset:6144
	ds_read_b128 v[216:219], v178 offset:7168
	s_waitcnt vmcnt(8)
	s_waitcnt lgkmcnt(0)
	s_barrier
	s_setprio 1
	s_waitcnt lgkmcnt(0)
	v_mfma_f32_16x16x32_bf16 v[124:127], v[128:131], v[188:191], v[124:127]
	v_mfma_f32_16x16x32_bf16 v[120:123], v[136:139], v[188:191], v[120:123]
	v_mfma_f32_16x16x32_bf16 v[108:111], v[128:131], v[196:199], v[108:111]
	v_mfma_f32_16x16x32_bf16 v[104:107], v[136:139], v[196:199], v[104:107]
	v_mfma_f32_16x16x32_bf16 v[92:95], v[128:131], v[204:207], v[92:95]
	v_mfma_f32_16x16x32_bf16 v[88:91], v[136:139], v[204:207], v[88:91]
	v_mfma_f32_16x16x32_bf16 v[76:79], v[128:131], v[212:215], v[76:79]
	v_mfma_f32_16x16x32_bf16 v[72:75], v[136:139], v[212:215], v[72:75]
	v_mfma_f32_16x16x32_bf16 v[124:127], v[132:135], v[192:195], v[124:127]
	v_mfma_f32_16x16x32_bf16 v[120:123], v[140:143], v[192:195], v[120:123]
	v_mfma_f32_16x16x32_bf16 v[108:111], v[132:135], v[200:203], v[108:111]
	v_mfma_f32_16x16x32_bf16 v[104:107], v[140:143], v[200:203], v[104:107]
	v_mfma_f32_16x16x32_bf16 v[92:95], v[132:135], v[208:211], v[92:95]
	v_mfma_f32_16x16x32_bf16 v[88:91], v[140:143], v[208:211], v[88:91]
	v_mfma_f32_16x16x32_bf16 v[76:79], v[132:135], v[216:219], v[76:79]
	v_mfma_f32_16x16x32_bf16 v[72:75], v[140:143], v[216:219], v[72:75]
	s_setprio 0
	s_setprio 1
	v_mfma_f32_16x16x32_bf16 v[116:119], v[144:147], v[188:191], v[116:119]
	v_mfma_f32_16x16x32_bf16 v[112:115], v[180:183], v[188:191], v[112:115]
	v_mfma_f32_16x16x32_bf16 v[100:103], v[144:147], v[196:199], v[100:103]
	v_mfma_f32_16x16x32_bf16 v[96:99], v[180:183], v[196:199], v[96:99]
	v_mfma_f32_16x16x32_bf16 v[84:87], v[144:147], v[204:207], v[84:87]
	v_mfma_f32_16x16x32_bf16 v[80:83], v[180:183], v[204:207], v[80:83]
	v_mfma_f32_16x16x32_bf16 v[68:71], v[144:147], v[212:215], v[68:71]
	v_mfma_f32_16x16x32_bf16 v[64:67], v[180:183], v[212:215], v[64:67]
	v_mfma_f32_16x16x32_bf16 v[116:119], v[148:151], v[192:195], v[116:119]
	v_mfma_f32_16x16x32_bf16 v[112:115], v[184:187], v[192:195], v[112:115]
	v_mfma_f32_16x16x32_bf16 v[100:103], v[148:151], v[200:203], v[100:103]
	v_mfma_f32_16x16x32_bf16 v[96:99], v[184:187], v[200:203], v[96:99]
	v_mfma_f32_16x16x32_bf16 v[84:87], v[148:151], v[208:211], v[84:87]
	v_mfma_f32_16x16x32_bf16 v[80:83], v[184:187], v[208:211], v[80:83]
	v_mfma_f32_16x16x32_bf16 v[68:71], v[148:151], v[216:219], v[68:71]
	v_mfma_f32_16x16x32_bf16 v[64:67], v[184:187], v[216:219], v[64:67]
	s_setprio 0
	s_barrier
	s_add_i32 s41, s68, s33
	v_lshl_add_u64 v[172:173], s[30:31], 0, v[154:155]
	s_mov_b32 m0, s41
	v_lshl_add_u64 v[220:221], s[30:31], 0, v[158:159]
	global_load_lds_dwordx4 v[172:173], off
	s_add_i32 m0, s41, 0x2000
	s_add_u32 s42, s30, 0x100000
	s_addc_u32 s43, s31, 0
	s_add_i32 s41, s69, s33
	global_load_lds_dwordx4 v[220:221], off
	v_lshl_add_u64 v[188:189], s[42:43], 0, v[154:155]
	s_mov_b32 m0, s41
	v_lshl_add_u64 v[222:223], s[34:35], 0, v[152:153]
	global_load_lds_dwordx4 v[188:189], off
	v_lshl_add_u64 v[188:189], s[42:43], 0, v[158:159]
	s_add_i32 m0, s41, 0x2000
	v_lshl_add_u64 v[224:225], s[34:35], 0, v[156:157]
	global_load_lds_dwordx4 v[188:189], off
	s_mov_b32 m0, s7
	s_nop 0
	global_load_lds_dwordx4 v[222:223], off
	s_mov_b32 m0, s59
	s_nop 0
	global_load_lds_dwordx4 v[224:225], off
	ds_read_b128 v[188:191], v178 offset:16384
	ds_read_b128 v[192:195], v178 offset:17408
	ds_read_b128 v[196:199], v178 offset:18432
	ds_read_b128 v[200:203], v178 offset:19456
	ds_read_b128 v[204:207], v178 offset:20480
	ds_read_b128 v[208:211], v178 offset:21504
	ds_read_b128 v[212:215], v178 offset:22528
	ds_read_b128 v[216:219], v178 offset:23552
	s_waitcnt vmcnt(8)
	s_waitcnt lgkmcnt(0)
	s_barrier
	s_setprio 1
	s_waitcnt lgkmcnt(0)
	v_mfma_f32_16x16x32_bf16 v[60:63], v[128:131], v[188:191], v[60:63]
	v_mfma_f32_16x16x32_bf16 v[56:59], v[136:139], v[188:191], v[56:59]
	v_mfma_f32_16x16x32_bf16 v[44:47], v[128:131], v[196:199], v[44:47]
	v_mfma_f32_16x16x32_bf16 v[40:43], v[136:139], v[196:199], v[40:43]
	v_mfma_f32_16x16x32_bf16 v[28:31], v[128:131], v[204:207], v[28:31]
	v_mfma_f32_16x16x32_bf16 v[24:27], v[136:139], v[204:207], v[24:27]
	v_mfma_f32_16x16x32_bf16 v[12:15], v[128:131], v[212:215], v[12:15]
	v_mfma_f32_16x16x32_bf16 v[8:11], v[136:139], v[212:215], v[8:11]
	v_mfma_f32_16x16x32_bf16 v[60:63], v[132:135], v[192:195], v[60:63]
	v_mfma_f32_16x16x32_bf16 v[56:59], v[140:143], v[192:195], v[56:59]
	v_mfma_f32_16x16x32_bf16 v[44:47], v[132:135], v[200:203], v[44:47]
	v_mfma_f32_16x16x32_bf16 v[40:43], v[140:143], v[200:203], v[40:43]
	v_mfma_f32_16x16x32_bf16 v[28:31], v[132:135], v[208:211], v[28:31]
	v_mfma_f32_16x16x32_bf16 v[24:27], v[140:143], v[208:211], v[24:27]
	v_mfma_f32_16x16x32_bf16 v[12:15], v[132:135], v[216:219], v[12:15]
	v_mfma_f32_16x16x32_bf16 v[8:11], v[140:143], v[216:219], v[8:11]
	s_setprio 0
	s_setprio 1
	v_mfma_f32_16x16x32_bf16 v[52:55], v[144:147], v[188:191], v[52:55]
	v_mfma_f32_16x16x32_bf16 v[48:51], v[180:183], v[188:191], v[48:51]
	v_mfma_f32_16x16x32_bf16 v[36:39], v[144:147], v[196:199], v[36:39]
	v_mfma_f32_16x16x32_bf16 v[32:35], v[180:183], v[196:199], v[32:35]
	v_mfma_f32_16x16x32_bf16 v[20:23], v[144:147], v[204:207], v[20:23]
	v_mfma_f32_16x16x32_bf16 v[16:19], v[180:183], v[204:207], v[16:19]
	v_mfma_f32_16x16x32_bf16 v[4:7], v[144:147], v[212:215], v[4:7]
	v_mfma_f32_16x16x32_bf16 v[0:3], v[180:183], v[212:215], v[0:3]
	v_mfma_f32_16x16x32_bf16 v[52:55], v[148:151], v[192:195], v[52:55]
	v_mfma_f32_16x16x32_bf16 v[48:51], v[184:187], v[192:195], v[48:51]
	v_mfma_f32_16x16x32_bf16 v[36:39], v[148:151], v[200:203], v[36:39]
	v_mfma_f32_16x16x32_bf16 v[32:35], v[184:187], v[200:203], v[32:35]
	v_mfma_f32_16x16x32_bf16 v[20:23], v[148:151], v[208:211], v[20:23]
	v_mfma_f32_16x16x32_bf16 v[16:19], v[184:187], v[208:211], v[16:19]
	v_mfma_f32_16x16x32_bf16 v[4:7], v[148:151], v[216:219], v[4:7]
	v_mfma_f32_16x16x32_bf16 v[0:3], v[184:187], v[216:219], v[0:3]
	s_setprio 0
	s_barrier
	s_add_i32 s41, 0, 0x18000
	s_add_i32 s42, 0, 0x1c000
	v_add_u32_e32 v140, s41, v174
	v_add_u32_e32 v184, s42, v174
	ds_read_b128 v[128:131], v140
	ds_read_b128 v[132:135], v140 offset:1024
	ds_read_b128 v[136:139], v140 offset:2048
	ds_read_b128 v[140:143], v140 offset:3072
	ds_read_b128 v[144:147], v184
	ds_read_b128 v[148:151], v184 offset:1024
	ds_read_b128 v[180:183], v184 offset:2048
	ds_read_b128 v[184:187], v184 offset:3072
	s_add_u32 s34, s34, 0x100000
	s_addc_u32 s35, s35, 0
	s_mov_b32 m0, s60
	v_lshl_add_u64 v[188:189], s[34:35], 0, v[152:153]
	global_load_lds_dwordx4 v[188:189], off
	v_lshl_add_u64 v[188:189], s[34:35], 0, v[156:157]
	s_mov_b32 m0, s61
	s_nop 0
	global_load_lds_dwordx4 v[188:189], off
	ds_read_b128 v[188:191], v178 offset:32768
	ds_read_b128 v[192:195], v178 offset:33792
	ds_read_b128 v[196:199], v178 offset:34816
	ds_read_b128 v[200:203], v178 offset:35840
	ds_read_b128 v[204:207], v178 offset:36864
	ds_read_b128 v[208:211], v178 offset:37888
	ds_read_b128 v[212:215], v178 offset:38912
	ds_read_b128 v[216:219], v178 offset:39936
	s_waitcnt vmcnt(8)
	s_waitcnt lgkmcnt(0)
	s_barrier
	s_setprio 1
	s_waitcnt lgkmcnt(0)
	v_mfma_f32_16x16x32_bf16 v[124:127], v[128:131], v[188:191], v[124:127]
	v_mfma_f32_16x16x32_bf16 v[120:123], v[136:139], v[188:191], v[120:123]
	v_mfma_f32_16x16x32_bf16 v[108:111], v[128:131], v[196:199], v[108:111]
	v_mfma_f32_16x16x32_bf16 v[104:107], v[136:139], v[196:199], v[104:107]
	v_mfma_f32_16x16x32_bf16 v[92:95], v[128:131], v[204:207], v[92:95]
	v_mfma_f32_16x16x32_bf16 v[88:91], v[136:139], v[204:207], v[88:91]
	v_mfma_f32_16x16x32_bf16 v[76:79], v[128:131], v[212:215], v[76:79]
	v_mfma_f32_16x16x32_bf16 v[72:75], v[136:139], v[212:215], v[72:75]
	v_mfma_f32_16x16x32_bf16 v[124:127], v[132:135], v[192:195], v[124:127]
	v_mfma_f32_16x16x32_bf16 v[120:123], v[140:143], v[192:195], v[120:123]
	v_mfma_f32_16x16x32_bf16 v[108:111], v[132:135], v[200:203], v[108:111]
	v_mfma_f32_16x16x32_bf16 v[104:107], v[140:143], v[200:203], v[104:107]
	v_mfma_f32_16x16x32_bf16 v[92:95], v[132:135], v[208:211], v[92:95]
	v_mfma_f32_16x16x32_bf16 v[88:91], v[140:143], v[208:211], v[88:91]
	v_mfma_f32_16x16x32_bf16 v[76:79], v[132:135], v[216:219], v[76:79]
	v_mfma_f32_16x16x32_bf16 v[72:75], v[140:143], v[216:219], v[72:75]
	s_setprio 0
	s_setprio 1
	v_mfma_f32_16x16x32_bf16 v[116:119], v[144:147], v[188:191], v[116:119]
	v_mfma_f32_16x16x32_bf16 v[112:115], v[180:183], v[188:191], v[112:115]
	v_mfma_f32_16x16x32_bf16 v[100:103], v[144:147], v[196:199], v[100:103]
	v_mfma_f32_16x16x32_bf16 v[96:99], v[180:183], v[196:199], v[96:99]
	v_mfma_f32_16x16x32_bf16 v[84:87], v[144:147], v[204:207], v[84:87]
	v_mfma_f32_16x16x32_bf16 v[80:83], v[180:183], v[204:207], v[80:83]
	v_mfma_f32_16x16x32_bf16 v[68:71], v[144:147], v[212:215], v[68:71]
	v_mfma_f32_16x16x32_bf16 v[64:67], v[180:183], v[212:215], v[64:67]
	v_mfma_f32_16x16x32_bf16 v[116:119], v[148:151], v[192:195], v[116:119]
	v_mfma_f32_16x16x32_bf16 v[112:115], v[184:187], v[192:195], v[112:115]
	v_mfma_f32_16x16x32_bf16 v[100:103], v[148:151], v[200:203], v[100:103]
	v_mfma_f32_16x16x32_bf16 v[96:99], v[184:187], v[200:203], v[96:99]
	v_mfma_f32_16x16x32_bf16 v[84:87], v[148:151], v[208:211], v[84:87]
	v_mfma_f32_16x16x32_bf16 v[80:83], v[184:187], v[208:211], v[80:83]
	v_mfma_f32_16x16x32_bf16 v[68:71], v[148:151], v[216:219], v[68:71]
	v_mfma_f32_16x16x32_bf16 v[64:67], v[184:187], v[216:219], v[64:67]
	s_setprio 0
	s_barrier
	s_add_i32 s34, s41, s33
	v_lshl_add_u64 v[172:173], v[172:173], 0, s[16:17]
	s_mov_b32 m0, s34
	s_nop 0
	global_load_lds_dwordx4 v[172:173], off
	s_add_i32 m0, s34, 0x2000
	s_add_u32 s30, s30, 0x100800
	v_lshl_add_u64 v[172:173], v[220:221], 0, s[16:17]
	s_addc_u32 s31, s31, 0
	s_add_i32 s34, s42, s33
	global_load_lds_dwordx4 v[172:173], off
	v_lshl_add_u64 v[172:173], s[30:31], 0, v[154:155]
	s_mov_b32 m0, s34
	s_nop 0
	global_load_lds_dwordx4 v[172:173], off
	v_lshl_add_u64 v[172:173], s[30:31], 0, v[158:159]
	s_add_i32 m0, s34, 0x2000
	s_nop 0
	global_load_lds_dwordx4 v[172:173], off
	v_lshl_add_u64 v[172:173], v[222:223], 0, s[18:19]
	s_mov_b32 m0, s63
	s_nop 0
	global_load_lds_dwordx4 v[172:173], off
	v_lshl_add_u64 v[172:173], v[224:225], 0, s[18:19]
	s_mov_b32 m0, s64
	s_nop 0
	global_load_lds_dwordx4 v[172:173], off
	ds_read_b128 v[188:191], v178 offset:49152
	ds_read_b128 v[192:195], v178 offset:50176
	ds_read_b128 v[196:199], v178 offset:51200
	ds_read_b128 v[200:203], v178 offset:52224
	ds_read_b128 v[204:207], v178 offset:53248
	ds_read_b128 v[208:211], v178 offset:54272
	ds_read_b128 v[212:215], v178 offset:55296
	ds_read_b128 v[216:219], v178 offset:56320
	s_waitcnt vmcnt(8)
	s_waitcnt lgkmcnt(0)
	s_barrier
	s_setprio 1
	s_waitcnt lgkmcnt(0)
	v_mfma_f32_16x16x32_bf16 v[60:63], v[128:131], v[188:191], v[60:63]
	v_mfma_f32_16x16x32_bf16 v[56:59], v[136:139], v[188:191], v[56:59]
	v_mfma_f32_16x16x32_bf16 v[44:47], v[128:131], v[196:199], v[44:47]
	v_mfma_f32_16x16x32_bf16 v[40:43], v[136:139], v[196:199], v[40:43]
	v_mfma_f32_16x16x32_bf16 v[28:31], v[128:131], v[204:207], v[28:31]
	v_mfma_f32_16x16x32_bf16 v[24:27], v[136:139], v[204:207], v[24:27]
	v_mfma_f32_16x16x32_bf16 v[12:15], v[128:131], v[212:215], v[12:15]
	v_mfma_f32_16x16x32_bf16 v[8:11], v[136:139], v[212:215], v[8:11]
	v_mfma_f32_16x16x32_bf16 v[60:63], v[132:135], v[192:195], v[60:63]
	v_mfma_f32_16x16x32_bf16 v[56:59], v[140:143], v[192:195], v[56:59]
	v_mfma_f32_16x16x32_bf16 v[44:47], v[132:135], v[200:203], v[44:47]
	v_mfma_f32_16x16x32_bf16 v[40:43], v[140:143], v[200:203], v[40:43]
	v_mfma_f32_16x16x32_bf16 v[28:31], v[132:135], v[208:211], v[28:31]
	v_mfma_f32_16x16x32_bf16 v[24:27], v[140:143], v[208:211], v[24:27]
	v_mfma_f32_16x16x32_bf16 v[12:15], v[132:135], v[216:219], v[12:15]
	v_mfma_f32_16x16x32_bf16 v[8:11], v[140:143], v[216:219], v[8:11]
	s_setprio 0
	s_setprio 1
	v_mfma_f32_16x16x32_bf16 v[52:55], v[144:147], v[188:191], v[52:55]
	v_mfma_f32_16x16x32_bf16 v[48:51], v[180:183], v[188:191], v[48:51]
	v_mfma_f32_16x16x32_bf16 v[36:39], v[144:147], v[196:199], v[36:39]
	v_mfma_f32_16x16x32_bf16 v[32:35], v[180:183], v[196:199], v[32:35]
	v_mfma_f32_16x16x32_bf16 v[20:23], v[144:147], v[204:207], v[20:23]
	v_mfma_f32_16x16x32_bf16 v[16:19], v[180:183], v[204:207], v[16:19]
	v_mfma_f32_16x16x32_bf16 v[4:7], v[144:147], v[212:215], v[4:7]
	v_mfma_f32_16x16x32_bf16 v[0:3], v[180:183], v[212:215], v[0:3]
	v_mfma_f32_16x16x32_bf16 v[52:55], v[148:151], v[192:195], v[52:55]
	v_mfma_f32_16x16x32_bf16 v[48:51], v[184:187], v[192:195], v[48:51]
	v_mfma_f32_16x16x32_bf16 v[36:39], v[148:151], v[200:203], v[36:39]
	v_mfma_f32_16x16x32_bf16 v[32:35], v[184:187], v[200:203], v[32:35]
	v_mfma_f32_16x16x32_bf16 v[20:23], v[148:151], v[208:211], v[20:23]
	v_mfma_f32_16x16x32_bf16 v[16:19], v[184:187], v[208:211], v[16:19]
	v_mfma_f32_16x16x32_bf16 v[4:7], v[148:151], v[216:219], v[4:7]
	v_mfma_f32_16x16x32_bf16 v[0:3], v[184:187], v[216:219], v[0:3]
	s_setprio 0
	s_barrier
	s_add_i32 s40, s40, 2
	s_add_u32 s38, s38, 0x1000
	s_addc_u32 s39, s39, 0
	s_add_u32 s28, s28, 0x100
	s_addc_u32 s29, s29, 0
	s_cmp_gt_u32 s40, 61
	s_cbranch_scc0 .LBB0_1202
	s_and_b64 vcc, exec, s[10:11]
	s_cbranch_vccz .LBB0_1205
	s_barrier

.LBB0_1263:
	ds_read_b128 v[146:149], v152
	ds_read_b128 v[156:159], v152 offset:1024
	ds_read_b128 v[160:163], v152 offset:2048
	ds_read_b128 v[164:167], v152 offset:3072
	ds_read_b128 v[168:171], v153
	ds_read_b128 v[172:175], v153 offset:1024
	ds_read_b128 v[176:179], v153 offset:2048
	ds_read_b128 v[180:183], v153 offset:3072
	s_add_u32 s22, s20, 0x100
	s_addc_u32 s23, s21, 0
	s_cmp_eq_u32 s46, 12
	s_cselect_b32 s27, s5, s23
	s_cselect_b32 s26, s4, s22
	s_cselect_b32 s25, s19, s15
	s_cselect_b32 s24, s18, s6
	v_lshl_add_u64 v[184:185], s[20:21], 0, v[136:137]
	s_add_i32 m0, s17, 0xc000
	s_nop 0
	global_load_lds_dwordx4 v[184:185], off
	v_lshl_add_u64 v[184:185], s[20:21], 0, v[138:139]
	s_add_i32 m0, s17, 0xe000
	s_nop 0
	global_load_lds_dwordx4 v[184:185], off
	ds_read_b128 v[184:187], v154
	ds_read_b128 v[188:191], v154 offset:1024
	ds_read_b128 v[192:195], v154 offset:2048
	ds_read_b128 v[196:199], v154 offset:3072
	ds_read_b128 v[200:203], v154 offset:4096
	ds_read_b128 v[204:207], v154 offset:5120
	ds_read_b128 v[208:211], v154 offset:6144
	ds_read_b128 v[212:215], v154 offset:7168
	s_waitcnt vmcnt(8)
	s_waitcnt lgkmcnt(0)
	s_barrier
	s_setprio 1
	s_waitcnt lgkmcnt(0)
	v_mfma_f32_16x16x32_bf16 v[124:127], v[146:149], v[184:187], v[124:127]
	v_mfma_f32_16x16x32_bf16 v[120:123], v[160:163], v[184:187], v[120:123]
	v_mfma_f32_16x16x32_bf16 v[112:115], v[146:149], v[192:195], v[112:115]
	v_mfma_f32_16x16x32_bf16 v[104:107], v[160:163], v[192:195], v[104:107]
	v_mfma_f32_16x16x32_bf16 v[96:99], v[146:149], v[200:203], v[96:99]
	v_mfma_f32_16x16x32_bf16 v[88:91], v[160:163], v[200:203], v[88:91]
	v_mfma_f32_16x16x32_bf16 v[80:83], v[146:149], v[208:211], v[80:83]
	v_mfma_f32_16x16x32_bf16 v[72:75], v[160:163], v[208:211], v[72:75]
	v_mfma_f32_16x16x32_bf16 v[124:127], v[156:159], v[188:191], v[124:127]
	v_mfma_f32_16x16x32_bf16 v[120:123], v[164:167], v[188:191], v[120:123]
	v_mfma_f32_16x16x32_bf16 v[112:115], v[156:159], v[196:199], v[112:115]
	v_mfma_f32_16x16x32_bf16 v[104:107], v[164:167], v[196:199], v[104:107]
	v_mfma_f32_16x16x32_bf16 v[96:99], v[156:159], v[204:207], v[96:99]
	v_mfma_f32_16x16x32_bf16 v[88:91], v[164:167], v[204:207], v[88:91]
	v_mfma_f32_16x16x32_bf16 v[80:83], v[156:159], v[212:215], v[80:83]
	v_mfma_f32_16x16x32_bf16 v[72:75], v[164:167], v[212:215], v[72:75]
	s_setprio 0
	s_setprio 1
	v_mfma_f32_16x16x32_bf16 v[116:119], v[168:171], v[184:187], v[116:119]
	v_mfma_f32_16x16x32_bf16 v[108:111], v[176:179], v[184:187], v[108:111]
	v_mfma_f32_16x16x32_bf16 v[100:103], v[168:171], v[192:195], v[100:103]
	v_mfma_f32_16x16x32_bf16 v[92:95], v[176:179], v[192:195], v[92:95]
	v_mfma_f32_16x16x32_bf16 v[84:87], v[168:171], v[200:203], v[84:87]
	v_mfma_f32_16x16x32_bf16 v[76:79], v[176:179], v[200:203], v[76:79]
	v_mfma_f32_16x16x32_bf16 v[68:71], v[168:171], v[208:211], v[68:71]
	v_mfma_f32_16x16x32_bf16 v[64:67], v[176:179], v[208:211], v[64:67]
	v_mfma_f32_16x16x32_bf16 v[116:119], v[172:175], v[188:191], v[116:119]
	v_mfma_f32_16x16x32_bf16 v[108:111], v[180:183], v[188:191], v[108:111]
	v_mfma_f32_16x16x32_bf16 v[100:103], v[172:175], v[196:199], v[100:103]
	v_mfma_f32_16x16x32_bf16 v[92:95], v[180:183], v[196:199], v[92:95]
	v_mfma_f32_16x16x32_bf16 v[84:87], v[172:175], v[204:207], v[84:87]
	v_mfma_f32_16x16x32_bf16 v[76:79], v[180:183], v[204:207], v[76:79]
	v_mfma_f32_16x16x32_bf16 v[68:71], v[172:175], v[212:215], v[68:71]
	v_mfma_f32_16x16x32_bf16 v[64:67], v[180:183], v[212:215], v[64:67]
	s_setprio 0
	s_barrier
	s_add_i32 s20, s41, s33
	v_lshl_add_u64 v[216:217], s[24:25], 0, v[130:131]
	s_mov_b32 m0, s20
	v_lshl_add_u64 v[218:219], s[24:25], 0, v[134:135]
	global_load_lds_dwordx4 v[216:217], off
	s_add_i32 m0, s20, 0x2000
	s_add_u32 s20, s24, 0x200000
	s_addc_u32 s21, s25, 0
	s_add_i32 s47, s42, s33
	global_load_lds_dwordx4 v[218:219], off
	v_lshl_add_u64 v[184:185], s[20:21], 0, v[130:131]
	s_mov_b32 m0, s47
	v_lshl_add_u64 v[220:221], s[26:27], 0, v[128:129]
	global_load_lds_dwordx4 v[184:185], off
	v_lshl_add_u64 v[184:185], s[20:21], 0, v[134:135]
	s_add_i32 m0, s47, 0x2000
	v_lshl_add_u64 v[222:223], s[26:27], 0, v[132:133]
	global_load_lds_dwordx4 v[184:185], off
	s_mov_b32 m0, s17
	s_nop 0
	global_load_lds_dwordx4 v[220:221], off
	s_mov_b32 m0, s34
	s_nop 0
	global_load_lds_dwordx4 v[222:223], off
	ds_read_b128 v[184:187], v154 offset:16384
	ds_read_b128 v[188:191], v154 offset:17408
	ds_read_b128 v[192:195], v154 offset:18432
	ds_read_b128 v[196:199], v154 offset:19456
	ds_read_b128 v[200:203], v154 offset:20480
	ds_read_b128 v[204:207], v154 offset:21504
	ds_read_b128 v[208:211], v154 offset:22528
	ds_read_b128 v[212:215], v154 offset:23552
	s_waitcnt vmcnt(8)
	s_waitcnt lgkmcnt(0)
	s_barrier
	s_setprio 1
	s_waitcnt lgkmcnt(0)
	v_mfma_f32_16x16x32_bf16 v[60:63], v[146:149], v[184:187], v[60:63]
	v_mfma_f32_16x16x32_bf16 v[56:59], v[160:163], v[184:187], v[56:59]
	v_mfma_f32_16x16x32_bf16 v[48:51], v[146:149], v[192:195], v[48:51]
	v_mfma_f32_16x16x32_bf16 v[40:43], v[160:163], v[192:195], v[40:43]
	v_mfma_f32_16x16x32_bf16 v[32:35], v[146:149], v[200:203], v[32:35]
	v_mfma_f32_16x16x32_bf16 v[24:27], v[160:163], v[200:203], v[24:27]
	v_mfma_f32_16x16x32_bf16 v[16:19], v[146:149], v[208:211], v[16:19]
	v_mfma_f32_16x16x32_bf16 v[8:11], v[160:163], v[208:211], v[8:11]
	v_mfma_f32_16x16x32_bf16 v[60:63], v[156:159], v[188:191], v[60:63]
	v_mfma_f32_16x16x32_bf16 v[56:59], v[164:167], v[188:191], v[56:59]
	v_mfma_f32_16x16x32_bf16 v[48:51], v[156:159], v[196:199], v[48:51]
	v_mfma_f32_16x16x32_bf16 v[40:43], v[164:167], v[196:199], v[40:43]
	v_mfma_f32_16x16x32_bf16 v[32:35], v[156:159], v[204:207], v[32:35]
	v_mfma_f32_16x16x32_bf16 v[24:27], v[164:167], v[204:207], v[24:27]
	v_mfma_f32_16x16x32_bf16 v[16:19], v[156:159], v[212:215], v[16:19]
	v_mfma_f32_16x16x32_bf16 v[8:11], v[164:167], v[212:215], v[8:11]
	s_setprio 0
	s_setprio 1
	v_mfma_f32_16x16x32_bf16 v[52:55], v[168:171], v[184:187], v[52:55]
	v_mfma_f32_16x16x32_bf16 v[44:47], v[176:179], v[184:187], v[44:47]
	v_mfma_f32_16x16x32_bf16 v[36:39], v[168:171], v[192:195], v[36:39]
	v_mfma_f32_16x16x32_bf16 v[28:31], v[176:179], v[192:195], v[28:31]
	v_mfma_f32_16x16x32_bf16 v[20:23], v[168:171], v[200:203], v[20:23]
	v_mfma_f32_16x16x32_bf16 v[12:15], v[176:179], v[200:203], v[12:15]
	v_mfma_f32_16x16x32_bf16 v[4:7], v[168:171], v[208:211], v[4:7]
	v_mfma_f32_16x16x32_bf16 v[0:3], v[176:179], v[208:211], v[0:3]
	v_mfma_f32_16x16x32_bf16 v[52:55], v[172:175], v[188:191], v[52:55]
	v_mfma_f32_16x16x32_bf16 v[44:47], v[180:183], v[188:191], v[44:47]
	v_mfma_f32_16x16x32_bf16 v[36:39], v[172:175], v[196:199], v[36:39]
	v_mfma_f32_16x16x32_bf16 v[28:31], v[180:183], v[196:199], v[28:31]
	v_mfma_f32_16x16x32_bf16 v[20:23], v[172:175], v[204:207], v[20:23]
	v_mfma_f32_16x16x32_bf16 v[12:15], v[180:183], v[204:207], v[12:15]
	v_mfma_f32_16x16x32_bf16 v[4:7], v[172:175], v[212:215], v[4:7]
	v_mfma_f32_16x16x32_bf16 v[0:3], v[180:183], v[212:215], v[0:3]
	s_setprio 0
	s_barrier
	s_add_i32 s47, 0, 0x18000
	v_add_u32_e32 v144, s47, v145
	s_add_i32 s48, 0, 0x1c000
	ds_read_b128 v[146:149], v144
	ds_read_b128 v[156:159], v144 offset:1024
	ds_read_b128 v[160:163], v144 offset:2048
	ds_read_b128 v[164:167], v144 offset:3072
	v_add_u32_e32 v144, s48, v145
	ds_read_b128 v[168:171], v144
	ds_read_b128 v[172:175], v144 offset:1024
	ds_read_b128 v[176:179], v144 offset:2048
	ds_read_b128 v[180:183], v144 offset:3072
	s_add_u32 s20, s26, 0x200000
	s_addc_u32 s21, s27, 0
	s_mov_b32 m0, s35
	v_lshl_add_u64 v[184:185], s[20:21], 0, v[128:129]
	global_load_lds_dwordx4 v[184:185], off
	v_lshl_add_u64 v[184:185], s[20:21], 0, v[132:133]
	s_mov_b32 m0, s36
	s_nop 0
	global_load_lds_dwordx4 v[184:185], off
	ds_read_b128 v[184:187], v154 offset:32768
	ds_read_b128 v[188:191], v154 offset:33792
	ds_read_b128 v[192:195], v154 offset:34816
	ds_read_b128 v[196:199], v154 offset:35840
	ds_read_b128 v[200:203], v154 offset:36864
	ds_read_b128 v[204:207], v154 offset:37888
	ds_read_b128 v[208:211], v154 offset:38912
	ds_read_b128 v[212:215], v154 offset:39936
	s_waitcnt vmcnt(8)
	s_waitcnt lgkmcnt(0)
	s_barrier
	s_setprio 1
	s_waitcnt lgkmcnt(0)
	v_mfma_f32_16x16x32_bf16 v[124:127], v[146:149], v[184:187], v[124:127]
	v_mfma_f32_16x16x32_bf16 v[120:123], v[160:163], v[184:187], v[120:123]
	v_mfma_f32_16x16x32_bf16 v[112:115], v[146:149], v[192:195], v[112:115]
	v_mfma_f32_16x16x32_bf16 v[104:107], v[160:163], v[192:195], v[104:107]
	v_mfma_f32_16x16x32_bf16 v[96:99], v[146:149], v[200:203], v[96:99]
	v_mfma_f32_16x16x32_bf16 v[88:91], v[160:163], v[200:203], v[88:91]
	v_mfma_f32_16x16x32_bf16 v[80:83], v[146:149], v[208:211], v[80:83]
	v_mfma_f32_16x16x32_bf16 v[72:75], v[160:163], v[208:211], v[72:75]
	v_mfma_f32_16x16x32_bf16 v[124:127], v[156:159], v[188:191], v[124:127]
	v_mfma_f32_16x16x32_bf16 v[120:123], v[164:167], v[188:191], v[120:123]
	v_mfma_f32_16x16x32_bf16 v[112:115], v[156:159], v[196:199], v[112:115]
	v_mfma_f32_16x16x32_bf16 v[104:107], v[164:167], v[196:199], v[104:107]
	v_mfma_f32_16x16x32_bf16 v[96:99], v[156:159], v[204:207], v[96:99]
	v_mfma_f32_16x16x32_bf16 v[88:91], v[164:167], v[204:207], v[88:91]
	v_mfma_f32_16x16x32_bf16 v[80:83], v[156:159], v[212:215], v[80:83]
	v_mfma_f32_16x16x32_bf16 v[72:75], v[164:167], v[212:215], v[72:75]
	s_setprio 0
	s_setprio 1
	v_mfma_f32_16x16x32_bf16 v[116:119], v[168:171], v[184:187], v[116:119]
	v_mfma_f32_16x16x32_bf16 v[108:111], v[176:179], v[184:187], v[108:111]
	v_mfma_f32_16x16x32_bf16 v[100:103], v[168:171], v[192:195], v[100:103]
	v_mfma_f32_16x16x32_bf16 v[92:95], v[176:179], v[192:195], v[92:95]
	v_mfma_f32_16x16x32_bf16 v[84:87], v[168:171], v[200:203], v[84:87]
	v_mfma_f32_16x16x32_bf16 v[76:79], v[176:179], v[200:203], v[76:79]
	v_mfma_f32_16x16x32_bf16 v[68:71], v[168:171], v[208:211], v[68:71]
	v_mfma_f32_16x16x32_bf16 v[64:67], v[176:179], v[208:211], v[64:67]
	v_mfma_f32_16x16x32_bf16 v[116:119], v[172:175], v[188:191], v[116:119]
	v_mfma_f32_16x16x32_bf16 v[108:111], v[180:183], v[188:191], v[108:111]
	v_mfma_f32_16x16x32_bf16 v[100:103], v[172:175], v[196:199], v[100:103]
	v_mfma_f32_16x16x32_bf16 v[92:95], v[180:183], v[196:199], v[92:95]
	v_mfma_f32_16x16x32_bf16 v[84:87], v[172:175], v[204:207], v[84:87]
	v_mfma_f32_16x16x32_bf16 v[76:79], v[180:183], v[204:207], v[76:79]
	v_mfma_f32_16x16x32_bf16 v[68:71], v[172:175], v[212:215], v[68:71]
	v_mfma_f32_16x16x32_bf16 v[64:67], v[180:183], v[212:215], v[64:67]
	s_setprio 0
	s_barrier
	s_add_i32 s20, s47, s33
	v_lshl_add_u64 v[184:185], v[216:217], 0, s[12:13]
	s_mov_b32 m0, s20
	s_nop 0
	global_load_lds_dwordx4 v[184:185], off
	s_add_i32 m0, s20, 0x2000
	s_add_u32 s20, s24, 0x200080
	v_lshl_add_u64 v[184:185], v[218:219], 0, s[12:13]
	s_addc_u32 s21, s25, 0
	s_add_i32 s24, s48, s33
	global_load_lds_dwordx4 v[184:185], off
	v_lshl_add_u64 v[184:185], s[20:21], 0, v[130:131]
	s_mov_b32 m0, s24
	s_nop 0
	global_load_lds_dwordx4 v[184:185], off
	v_lshl_add_u64 v[184:185], s[20:21], 0, v[134:135]
	s_add_i32 m0, s24, 0x2000
	s_nop 0
	global_load_lds_dwordx4 v[184:185], off
	v_lshl_add_u64 v[184:185], v[220:221], 0, s[12:13]
	s_mov_b32 m0, s37
	s_nop 0
	global_load_lds_dwordx4 v[184:185], off
	v_lshl_add_u64 v[184:185], v[222:223], 0, s[12:13]
	s_mov_b32 m0, s38
	s_nop 0
	global_load_lds_dwordx4 v[184:185], off
	ds_read_b128 v[184:187], v154 offset:49152
	ds_read_b128 v[188:191], v154 offset:50176
	ds_read_b128 v[192:195], v154 offset:51200
	ds_read_b128 v[196:199], v154 offset:52224
	ds_read_b128 v[200:203], v154 offset:53248
	ds_read_b128 v[204:207], v154 offset:54272
	ds_read_b128 v[208:211], v154 offset:55296
	ds_read_b128 v[212:215], v154 offset:56320
	s_waitcnt vmcnt(8)
	s_waitcnt lgkmcnt(0)
	s_barrier
	s_setprio 1
	s_waitcnt lgkmcnt(0)
	v_mfma_f32_16x16x32_bf16 v[60:63], v[146:149], v[184:187], v[60:63]
	v_mfma_f32_16x16x32_bf16 v[56:59], v[160:163], v[184:187], v[56:59]
	v_mfma_f32_16x16x32_bf16 v[48:51], v[146:149], v[192:195], v[48:51]
	v_mfma_f32_16x16x32_bf16 v[40:43], v[160:163], v[192:195], v[40:43]
	v_mfma_f32_16x16x32_bf16 v[32:35], v[146:149], v[200:203], v[32:35]
	v_mfma_f32_16x16x32_bf16 v[24:27], v[160:163], v[200:203], v[24:27]
	v_mfma_f32_16x16x32_bf16 v[16:19], v[146:149], v[208:211], v[16:19]
	v_mfma_f32_16x16x32_bf16 v[8:11], v[160:163], v[208:211], v[8:11]
	v_mfma_f32_16x16x32_bf16 v[60:63], v[156:159], v[188:191], v[60:63]
	v_mfma_f32_16x16x32_bf16 v[56:59], v[164:167], v[188:191], v[56:59]
	v_mfma_f32_16x16x32_bf16 v[48:51], v[156:159], v[196:199], v[48:51]
	v_mfma_f32_16x16x32_bf16 v[40:43], v[164:167], v[196:199], v[40:43]
	v_mfma_f32_16x16x32_bf16 v[32:35], v[156:159], v[204:207], v[32:35]
	v_mfma_f32_16x16x32_bf16 v[24:27], v[164:167], v[204:207], v[24:27]
	v_mfma_f32_16x16x32_bf16 v[16:19], v[156:159], v[212:215], v[16:19]
	v_mfma_f32_16x16x32_bf16 v[8:11], v[164:167], v[212:215], v[8:11]
	s_setprio 0
	s_setprio 1
	v_mfma_f32_16x16x32_bf16 v[52:55], v[168:171], v[184:187], v[52:55]
	v_mfma_f32_16x16x32_bf16 v[44:47], v[176:179], v[184:187], v[44:47]
	v_mfma_f32_16x16x32_bf16 v[36:39], v[168:171], v[192:195], v[36:39]
	v_mfma_f32_16x16x32_bf16 v[28:31], v[176:179], v[192:195], v[28:31]
	v_mfma_f32_16x16x32_bf16 v[20:23], v[168:171], v[200:203], v[20:23]
	v_mfma_f32_16x16x32_bf16 v[12:15], v[176:179], v[200:203], v[12:15]
	v_mfma_f32_16x16x32_bf16 v[4:7], v[168:171], v[208:211], v[4:7]
	v_mfma_f32_16x16x32_bf16 v[0:3], v[176:179], v[208:211], v[0:3]
	v_mfma_f32_16x16x32_bf16 v[52:55], v[172:175], v[188:191], v[52:55]
	v_mfma_f32_16x16x32_bf16 v[44:47], v[180:183], v[188:191], v[44:47]
	v_mfma_f32_16x16x32_bf16 v[36:39], v[172:175], v[196:199], v[36:39]
	v_mfma_f32_16x16x32_bf16 v[28:31], v[180:183], v[196:199], v[28:31]
	v_mfma_f32_16x16x32_bf16 v[20:23], v[172:175], v[204:207], v[20:23]
	v_mfma_f32_16x16x32_bf16 v[12:15], v[180:183], v[204:207], v[12:15]
	v_mfma_f32_16x16x32_bf16 v[4:7], v[172:175], v[212:215], v[4:7]
	v_mfma_f32_16x16x32_bf16 v[0:3], v[180:183], v[212:215], v[0:3]
	s_setprio 0
	s_barrier
	s_add_i32 s46, s46, 2
	s_add_u32 s6, s6, 0x100
	s_addc_u32 s15, s15, 0
	s_cmp_gt_u32 s46, 13
	s_mov_b64 s[20:21], s[22:23]
	s_cbranch_scc0 .LBB0_1263
	s_and_b64 vcc, exec, s[8:9]
	s_cbranch_vccz .LBB0_1266
	s_barrier

.LBB0_1340:
	v_add_u32_e32 v166, s51, v152
	v_add_u32_e32 v182, s52, v152
	ds_read_b128 v[154:157], v166
	ds_read_b128 v[158:161], v166 offset:1024
	ds_read_b128 v[162:165], v166 offset:2048
	ds_read_b128 v[166:169], v166 offset:3072
	ds_read_b128 v[170:173], v182
	ds_read_b128 v[174:177], v182 offset:1024
	ds_read_b128 v[178:181], v182 offset:2048
	ds_read_b128 v[182:185], v182 offset:3072
	s_add_u32 s30, s10, s28
	s_addc_u32 s31, s11, s29
	s_cmp_eq_u32 s58, 60
	s_cselect_b32 s35, s23, s31
	s_cselect_b32 s34, s54, s30
	s_cselect_b32 s31, s21, s57
	s_cselect_b32 s30, s55, s56
	v_lshl_add_u64 v[186:187], s[10:11], 0, v[146:147]
	s_add_i32 m0, s44, 0xc000
	s_nop 0
	global_load_lds_dwordx4 v[186:187], off
	v_lshl_add_u64 v[186:187], s[10:11], 0, v[144:145]
	s_add_i32 m0, s44, 0xe000
	s_nop 0
	global_load_lds_dwordx4 v[186:187], off
	ds_read_b128 v[186:189], v153
	ds_read_b128 v[190:193], v153 offset:1024
	ds_read_b128 v[194:197], v153 offset:2048
	ds_read_b128 v[198:201], v153 offset:3072
	ds_read_b128 v[202:205], v153 offset:4096
	ds_read_b128 v[206:209], v153 offset:5120
	ds_read_b128 v[210:213], v153 offset:6144
	ds_read_b128 v[214:217], v153 offset:7168
	s_waitcnt vmcnt(8)
	s_waitcnt lgkmcnt(0)
	s_barrier
	s_setprio 1
	s_waitcnt lgkmcnt(0)
	v_mfma_f32_16x16x32_bf16 v[124:127], v[154:157], v[186:189], v[124:127]
	v_mfma_f32_16x16x32_bf16 v[120:123], v[162:165], v[186:189], v[120:123]
	v_mfma_f32_16x16x32_bf16 v[108:111], v[154:157], v[194:197], v[108:111]
	v_mfma_f32_16x16x32_bf16 v[104:107], v[162:165], v[194:197], v[104:107]
	v_mfma_f32_16x16x32_bf16 v[92:95], v[154:157], v[202:205], v[92:95]
	v_mfma_f32_16x16x32_bf16 v[88:91], v[162:165], v[202:205], v[88:91]
	v_mfma_f32_16x16x32_bf16 v[76:79], v[154:157], v[210:213], v[76:79]
	v_mfma_f32_16x16x32_bf16 v[72:75], v[162:165], v[210:213], v[72:75]
	v_mfma_f32_16x16x32_bf16 v[124:127], v[158:161], v[190:193], v[124:127]
	v_mfma_f32_16x16x32_bf16 v[120:123], v[166:169], v[190:193], v[120:123]
	v_mfma_f32_16x16x32_bf16 v[108:111], v[158:161], v[198:201], v[108:111]
	v_mfma_f32_16x16x32_bf16 v[104:107], v[166:169], v[198:201], v[104:107]
	v_mfma_f32_16x16x32_bf16 v[92:95], v[158:161], v[206:209], v[92:95]
	v_mfma_f32_16x16x32_bf16 v[88:91], v[166:169], v[206:209], v[88:91]
	v_mfma_f32_16x16x32_bf16 v[76:79], v[158:161], v[214:217], v[76:79]
	v_mfma_f32_16x16x32_bf16 v[72:75], v[166:169], v[214:217], v[72:75]
	s_setprio 0
	s_setprio 1
	v_mfma_f32_16x16x32_bf16 v[116:119], v[170:173], v[186:189], v[116:119]
	v_mfma_f32_16x16x32_bf16 v[112:115], v[178:181], v[186:189], v[112:115]
	v_mfma_f32_16x16x32_bf16 v[100:103], v[170:173], v[194:197], v[100:103]
	v_mfma_f32_16x16x32_bf16 v[96:99], v[178:181], v[194:197], v[96:99]
	v_mfma_f32_16x16x32_bf16 v[84:87], v[170:173], v[202:205], v[84:87]
	v_mfma_f32_16x16x32_bf16 v[80:83], v[178:181], v[202:205], v[80:83]
	v_mfma_f32_16x16x32_bf16 v[68:71], v[170:173], v[210:213], v[68:71]
	v_mfma_f32_16x16x32_bf16 v[64:67], v[178:181], v[210:213], v[64:67]
	v_mfma_f32_16x16x32_bf16 v[116:119], v[174:177], v[190:193], v[116:119]
	v_mfma_f32_16x16x32_bf16 v[112:115], v[182:185], v[190:193], v[112:115]
	v_mfma_f32_16x16x32_bf16 v[100:103], v[174:177], v[198:201], v[100:103]
	v_mfma_f32_16x16x32_bf16 v[96:99], v[182:185], v[198:201], v[96:99]
	v_mfma_f32_16x16x32_bf16 v[84:87], v[174:177], v[206:209], v[84:87]
	v_mfma_f32_16x16x32_bf16 v[80:83], v[182:185], v[206:209], v[80:83]
	v_mfma_f32_16x16x32_bf16 v[68:71], v[174:177], v[214:217], v[68:71]
	v_mfma_f32_16x16x32_bf16 v[64:67], v[182:185], v[214:217], v[64:67]
	s_setprio 0
	s_barrier
	s_add_i32 s59, s51, s43
	v_lshl_add_u64 v[218:219], s[30:31], 0, v[130:131]
	s_mov_b32 m0, s59
	v_lshl_add_u64 v[220:221], s[30:31], 0, v[134:135]
	global_load_lds_dwordx4 v[218:219], off
	s_add_i32 m0, s59, 0x2000
	s_add_u32 s60, s30, 0x100000
	s_addc_u32 s61, s31, 0
	s_add_i32 s59, s52, s43
	global_load_lds_dwordx4 v[220:221], off
	v_lshl_add_u64 v[186:187], s[60:61], 0, v[130:131]
	s_mov_b32 m0, s59
	v_lshl_add_u64 v[222:223], s[34:35], 0, v[128:129]
	global_load_lds_dwordx4 v[186:187], off
	v_lshl_add_u64 v[186:187], s[60:61], 0, v[134:135]
	s_add_i32 m0, s59, 0x2000
	v_lshl_add_u64 v[224:225], s[34:35], 0, v[132:133]
	global_load_lds_dwordx4 v[186:187], off
	s_mov_b32 m0, s44
	s_nop 0
	global_load_lds_dwordx4 v[222:223], off
	s_mov_b32 m0, s45
	s_nop 0
	global_load_lds_dwordx4 v[224:225], off
	ds_read_b128 v[186:189], v153 offset:16384
	ds_read_b128 v[190:193], v153 offset:17408
	ds_read_b128 v[194:197], v153 offset:18432
	ds_read_b128 v[198:201], v153 offset:19456
	ds_read_b128 v[202:205], v153 offset:20480
	ds_read_b128 v[206:209], v153 offset:21504
	ds_read_b128 v[210:213], v153 offset:22528
	ds_read_b128 v[214:217], v153 offset:23552
	s_waitcnt vmcnt(8)
	s_waitcnt lgkmcnt(0)
	s_barrier
	s_setprio 1
	s_waitcnt lgkmcnt(0)
	v_mfma_f32_16x16x32_bf16 v[60:63], v[154:157], v[186:189], v[60:63]
	v_mfma_f32_16x16x32_bf16 v[56:59], v[162:165], v[186:189], v[56:59]
	v_mfma_f32_16x16x32_bf16 v[44:47], v[154:157], v[194:197], v[44:47]
	v_mfma_f32_16x16x32_bf16 v[40:43], v[162:165], v[194:197], v[40:43]
	v_mfma_f32_16x16x32_bf16 v[28:31], v[154:157], v[202:205], v[28:31]
	v_mfma_f32_16x16x32_bf16 v[24:27], v[162:165], v[202:205], v[24:27]
	v_mfma_f32_16x16x32_bf16 v[12:15], v[154:157], v[210:213], v[12:15]
	v_mfma_f32_16x16x32_bf16 v[8:11], v[162:165], v[210:213], v[8:11]
	v_mfma_f32_16x16x32_bf16 v[60:63], v[158:161], v[190:193], v[60:63]
	v_mfma_f32_16x16x32_bf16 v[56:59], v[166:169], v[190:193], v[56:59]
	v_mfma_f32_16x16x32_bf16 v[44:47], v[158:161], v[198:201], v[44:47]
	v_mfma_f32_16x16x32_bf16 v[40:43], v[166:169], v[198:201], v[40:43]
	v_mfma_f32_16x16x32_bf16 v[28:31], v[158:161], v[206:209], v[28:31]
	v_mfma_f32_16x16x32_bf16 v[24:27], v[166:169], v[206:209], v[24:27]
	v_mfma_f32_16x16x32_bf16 v[12:15], v[158:161], v[214:217], v[12:15]
	v_mfma_f32_16x16x32_bf16 v[8:11], v[166:169], v[214:217], v[8:11]
	s_setprio 0
	s_setprio 1
	v_mfma_f32_16x16x32_bf16 v[52:55], v[170:173], v[186:189], v[52:55]
	v_mfma_f32_16x16x32_bf16 v[48:51], v[178:181], v[186:189], v[48:51]
	v_mfma_f32_16x16x32_bf16 v[36:39], v[170:173], v[194:197], v[36:39]
	v_mfma_f32_16x16x32_bf16 v[32:35], v[178:181], v[194:197], v[32:35]
	v_mfma_f32_16x16x32_bf16 v[20:23], v[170:173], v[202:205], v[20:23]
	v_mfma_f32_16x16x32_bf16 v[16:19], v[178:181], v[202:205], v[16:19]
	v_mfma_f32_16x16x32_bf16 v[4:7], v[170:173], v[210:213], v[4:7]
	v_mfma_f32_16x16x32_bf16 v[0:3], v[178:181], v[210:213], v[0:3]
	v_mfma_f32_16x16x32_bf16 v[52:55], v[174:177], v[190:193], v[52:55]
	v_mfma_f32_16x16x32_bf16 v[48:51], v[182:185], v[190:193], v[48:51]
	v_mfma_f32_16x16x32_bf16 v[36:39], v[174:177], v[198:201], v[36:39]
	v_mfma_f32_16x16x32_bf16 v[32:35], v[182:185], v[198:201], v[32:35]
	v_mfma_f32_16x16x32_bf16 v[20:23], v[174:177], v[206:209], v[20:23]
	v_mfma_f32_16x16x32_bf16 v[16:19], v[182:185], v[206:209], v[16:19]
	v_mfma_f32_16x16x32_bf16 v[4:7], v[174:177], v[214:217], v[4:7]
	v_mfma_f32_16x16x32_bf16 v[0:3], v[182:185], v[214:217], v[0:3]
	s_setprio 0
	s_barrier
	s_add_i32 s59, 0, 0x18000
	s_add_i32 s60, 0, 0x1c000
	v_add_u32_e32 v166, s59, v152
	v_add_u32_e32 v182, s60, v152
	ds_read_b128 v[154:157], v166
	ds_read_b128 v[158:161], v166 offset:1024
	ds_read_b128 v[162:165], v166 offset:2048
	ds_read_b128 v[166:169], v166 offset:3072
	ds_read_b128 v[170:173], v182
	ds_read_b128 v[174:177], v182 offset:1024
	ds_read_b128 v[178:181], v182 offset:2048
	ds_read_b128 v[182:185], v182 offset:3072
	s_add_u32 s34, s34, 0x100000
	s_addc_u32 s35, s35, 0
	s_mov_b32 m0, s46
	v_lshl_add_u64 v[186:187], s[34:35], 0, v[128:129]
	global_load_lds_dwordx4 v[186:187], off
	v_lshl_add_u64 v[186:187], s[34:35], 0, v[132:133]
	s_mov_b32 m0, s47
	s_nop 0
	global_load_lds_dwordx4 v[186:187], off
	ds_read_b128 v[186:189], v153 offset:32768
	ds_read_b128 v[190:193], v153 offset:33792
	ds_read_b128 v[194:197], v153 offset:34816
	ds_read_b128 v[198:201], v153 offset:35840
	ds_read_b128 v[202:205], v153 offset:36864
	ds_read_b128 v[206:209], v153 offset:37888
	ds_read_b128 v[210:213], v153 offset:38912
	ds_read_b128 v[214:217], v153 offset:39936
	s_waitcnt vmcnt(8)
	s_waitcnt lgkmcnt(0)
	s_barrier
	s_setprio 1
	s_waitcnt lgkmcnt(0)
	v_mfma_f32_16x16x32_bf16 v[124:127], v[154:157], v[186:189], v[124:127]
	v_mfma_f32_16x16x32_bf16 v[120:123], v[162:165], v[186:189], v[120:123]
	v_mfma_f32_16x16x32_bf16 v[108:111], v[154:157], v[194:197], v[108:111]
	v_mfma_f32_16x16x32_bf16 v[104:107], v[162:165], v[194:197], v[104:107]
	v_mfma_f32_16x16x32_bf16 v[92:95], v[154:157], v[202:205], v[92:95]
	v_mfma_f32_16x16x32_bf16 v[88:91], v[162:165], v[202:205], v[88:91]
	v_mfma_f32_16x16x32_bf16 v[76:79], v[154:157], v[210:213], v[76:79]
	v_mfma_f32_16x16x32_bf16 v[72:75], v[162:165], v[210:213], v[72:75]
	v_mfma_f32_16x16x32_bf16 v[124:127], v[158:161], v[190:193], v[124:127]
	v_mfma_f32_16x16x32_bf16 v[120:123], v[166:169], v[190:193], v[120:123]
	v_mfma_f32_16x16x32_bf16 v[108:111], v[158:161], v[198:201], v[108:111]
	v_mfma_f32_16x16x32_bf16 v[104:107], v[166:169], v[198:201], v[104:107]
	v_mfma_f32_16x16x32_bf16 v[92:95], v[158:161], v[206:209], v[92:95]
	v_mfma_f32_16x16x32_bf16 v[88:91], v[166:169], v[206:209], v[88:91]
	v_mfma_f32_16x16x32_bf16 v[76:79], v[158:161], v[214:217], v[76:79]
	v_mfma_f32_16x16x32_bf16 v[72:75], v[166:169], v[214:217], v[72:75]
	s_setprio 0
	s_setprio 1
	v_mfma_f32_16x16x32_bf16 v[116:119], v[170:173], v[186:189], v[116:119]
	v_mfma_f32_16x16x32_bf16 v[112:115], v[178:181], v[186:189], v[112:115]
	v_mfma_f32_16x16x32_bf16 v[100:103], v[170:173], v[194:197], v[100:103]
	v_mfma_f32_16x16x32_bf16 v[96:99], v[178:181], v[194:197], v[96:99]
	v_mfma_f32_16x16x32_bf16 v[84:87], v[170:173], v[202:205], v[84:87]
	v_mfma_f32_16x16x32_bf16 v[80:83], v[178:181], v[202:205], v[80:83]
	v_mfma_f32_16x16x32_bf16 v[68:71], v[170:173], v[210:213], v[68:71]
	v_mfma_f32_16x16x32_bf16 v[64:67], v[178:181], v[210:213], v[64:67]
	v_mfma_f32_16x16x32_bf16 v[116:119], v[174:177], v[190:193], v[116:119]
	v_mfma_f32_16x16x32_bf16 v[112:115], v[182:185], v[190:193], v[112:115]
	v_mfma_f32_16x16x32_bf16 v[100:103], v[174:177], v[198:201], v[100:103]
	v_mfma_f32_16x16x32_bf16 v[96:99], v[182:185], v[198:201], v[96:99]
	v_mfma_f32_16x16x32_bf16 v[84:87], v[174:177], v[206:209], v[84:87]
	v_mfma_f32_16x16x32_bf16 v[80:83], v[182:185], v[206:209], v[80:83]
	v_mfma_f32_16x16x32_bf16 v[68:71], v[174:177], v[214:217], v[68:71]
	v_mfma_f32_16x16x32_bf16 v[64:67], v[182:185], v[214:217], v[64:67]
	s_setprio 0
	s_barrier
	s_add_i32 s34, s59, s43
	v_lshl_add_u64 v[186:187], v[218:219], 0, s[14:15]
	s_mov_b32 m0, s34
	s_nop 0
	global_load_lds_dwordx4 v[186:187], off
	s_add_i32 m0, s34, 0x2000
	s_add_u32 s30, s30, 0x100080
	v_lshl_add_u64 v[186:187], v[220:221], 0, s[14:15]
	s_addc_u32 s31, s31, 0
	s_add_i32 s34, s60, s43
	global_load_lds_dwordx4 v[186:187], off
	v_lshl_add_u64 v[186:187], s[30:31], 0, v[130:131]
	s_mov_b32 m0, s34
	s_nop 0
	global_load_lds_dwordx4 v[186:187], off
	v_lshl_add_u64 v[186:187], s[30:31], 0, v[134:135]
	s_add_i32 m0, s34, 0x2000
	s_nop 0
	global_load_lds_dwordx4 v[186:187], off
	v_lshl_add_u64 v[186:187], v[222:223], 0, s[16:17]
	s_mov_b32 m0, s49
	s_nop 0
	global_load_lds_dwordx4 v[186:187], off
	v_lshl_add_u64 v[186:187], v[224:225], 0, s[16:17]
	s_mov_b32 m0, s50
	s_nop 0
	global_load_lds_dwordx4 v[186:187], off
	ds_read_b128 v[186:189], v153 offset:49152
	ds_read_b128 v[190:193], v153 offset:50176
	ds_read_b128 v[194:197], v153 offset:51200
	ds_read_b128 v[198:201], v153 offset:52224
	ds_read_b128 v[202:205], v153 offset:53248
	ds_read_b128 v[206:209], v153 offset:54272
	ds_read_b128 v[210:213], v153 offset:55296
	ds_read_b128 v[214:217], v153 offset:56320
	s_waitcnt vmcnt(8)
	s_waitcnt lgkmcnt(0)
	s_barrier
	s_setprio 1
	s_waitcnt lgkmcnt(0)
	v_mfma_f32_16x16x32_bf16 v[60:63], v[154:157], v[186:189], v[60:63]
	v_mfma_f32_16x16x32_bf16 v[56:59], v[162:165], v[186:189], v[56:59]
	v_mfma_f32_16x16x32_bf16 v[44:47], v[154:157], v[194:197], v[44:47]
	v_mfma_f32_16x16x32_bf16 v[40:43], v[162:165], v[194:197], v[40:43]
	v_mfma_f32_16x16x32_bf16 v[28:31], v[154:157], v[202:205], v[28:31]
	v_mfma_f32_16x16x32_bf16 v[24:27], v[162:165], v[202:205], v[24:27]
	v_mfma_f32_16x16x32_bf16 v[12:15], v[154:157], v[210:213], v[12:15]
	v_mfma_f32_16x16x32_bf16 v[8:11], v[162:165], v[210:213], v[8:11]
	v_mfma_f32_16x16x32_bf16 v[60:63], v[158:161], v[190:193], v[60:63]
	v_mfma_f32_16x16x32_bf16 v[56:59], v[166:169], v[190:193], v[56:59]
	v_mfma_f32_16x16x32_bf16 v[44:47], v[158:161], v[198:201], v[44:47]
	v_mfma_f32_16x16x32_bf16 v[40:43], v[166:169], v[198:201], v[40:43]
	v_mfma_f32_16x16x32_bf16 v[28:31], v[158:161], v[206:209], v[28:31]
	v_mfma_f32_16x16x32_bf16 v[24:27], v[166:169], v[206:209], v[24:27]
	v_mfma_f32_16x16x32_bf16 v[12:15], v[158:161], v[214:217], v[12:15]
	v_mfma_f32_16x16x32_bf16 v[8:11], v[166:169], v[214:217], v[8:11]
	s_setprio 0
	s_setprio 1
	v_mfma_f32_16x16x32_bf16 v[52:55], v[170:173], v[186:189], v[52:55]
	v_mfma_f32_16x16x32_bf16 v[48:51], v[178:181], v[186:189], v[48:51]
	v_mfma_f32_16x16x32_bf16 v[36:39], v[170:173], v[194:197], v[36:39]
	v_mfma_f32_16x16x32_bf16 v[32:35], v[178:181], v[194:197], v[32:35]
	v_mfma_f32_16x16x32_bf16 v[20:23], v[170:173], v[202:205], v[20:23]
	v_mfma_f32_16x16x32_bf16 v[16:19], v[178:181], v[202:205], v[16:19]
	v_mfma_f32_16x16x32_bf16 v[4:7], v[170:173], v[210:213], v[4:7]
	v_mfma_f32_16x16x32_bf16 v[0:3], v[178:181], v[210:213], v[0:3]
	v_mfma_f32_16x16x32_bf16 v[52:55], v[174:177], v[190:193], v[52:55]
	v_mfma_f32_16x16x32_bf16 v[48:51], v[182:185], v[190:193], v[48:51]
	v_mfma_f32_16x16x32_bf16 v[36:39], v[174:177], v[198:201], v[36:39]
	v_mfma_f32_16x16x32_bf16 v[32:35], v[182:185], v[198:201], v[32:35]
	v_mfma_f32_16x16x32_bf16 v[20:23], v[174:177], v[206:209], v[20:23]
	v_mfma_f32_16x16x32_bf16 v[16:19], v[182:185], v[206:209], v[16:19]
	v_mfma_f32_16x16x32_bf16 v[4:7], v[174:177], v[214:217], v[4:7]
	v_mfma_f32_16x16x32_bf16 v[0:3], v[182:185], v[214:217], v[0:3]
	s_setprio 0
	s_barrier
	s_add_i32 s58, s58, 2
	s_add_u32 s56, s56, 0x100
	s_addc_u32 s57, s57, 0
	s_add_u32 s28, s28, 0x1000
	s_addc_u32 s29, s29, 0
	v_lshl_add_u64 v[146:147], v[146:147], 0, s[18:19]
	s_cmp_gt_u32 s58, 61
	v_lshl_add_u64 v[144:145], v[144:145], 0, s[18:19]
	s_cbranch_scc0 .LBB0_1340
	s_andn2_b64 vcc, exec, s[4:5]
	s_cbranch_vccnz .LBB0_1332
	v_mov_b32_e32 v0, 0
	s_mov_b32 s7, s20
	s_mov_b32 s6, s22
	s_mov_b64 s[8:9], s[26:27]
	s_mov_b64 s[10:11], s[24:25]
	s_mov_b32 s48, s53
	v_mov_b32_e32 v1, v0
	v_mov_b32_e32 v2, v0
	v_mov_b32_e32 v3, v0
	v_mov_b32_e32 v4, v0
	v_mov_b32_e32 v5, v0
	v_mov_b32_e32 v6, v0
	v_mov_b32_e32 v7, v0
	v_mov_b32_e32 v16, v0
	v_mov_b32_e32 v17, v0
	v_mov_b32_e32 v18, v0
	v_mov_b32_e32 v19, v0
	v_mov_b32_e32 v20, v0
	v_mov_b32_e32 v21, v0
	v_mov_b32_e32 v22, v0
	v_mov_b32_e32 v23, v0
	v_mov_b32_e32 v32, v0
	v_mov_b32_e32 v33, v0
	v_mov_b32_e32 v34, v0
	v_mov_b32_e32 v35, v0
	v_mov_b32_e32 v36, v0
	v_mov_b32_e32 v37, v0
	v_mov_b32_e32 v38, v0
	v_mov_b32_e32 v39, v0
	v_mov_b32_e32 v48, v0
	v_mov_b32_e32 v49, v0
	v_mov_b32_e32 v50, v0
	v_mov_b32_e32 v51, v0
	v_mov_b32_e32 v52, v0
	v_mov_b32_e32 v53, v0
	v_mov_b32_e32 v54, v0
	v_mov_b32_e32 v55, v0
	v_mov_b32_e32 v8, v0
	v_mov_b32_e32 v9, v0
	v_mov_b32_e32 v10, v0
	v_mov_b32_e32 v11, v0
	v_mov_b32_e32 v12, v0
	v_mov_b32_e32 v13, v0
	v_mov_b32_e32 v14, v0
	v_mov_b32_e32 v15, v0
	v_mov_b32_e32 v24, v0
	v_mov_b32_e32 v25, v0
	v_mov_b32_e32 v26, v0
	v_mov_b32_e32 v27, v0
	v_mov_b32_e32 v28, v0
	v_mov_b32_e32 v29, v0
	v_mov_b32_e32 v30, v0
	v_mov_b32_e32 v31, v0
	v_mov_b32_e32 v40, v0
	v_mov_b32_e32 v41, v0
	v_mov_b32_e32 v42, v0
	v_mov_b32_e32 v43, v0
	v_mov_b32_e32 v44, v0
	v_mov_b32_e32 v45, v0
	v_mov_b32_e32 v46, v0
	v_mov_b32_e32 v47, v0
	v_mov_b32_e32 v56, v0
	v_mov_b32_e32 v57, v0
	v_mov_b32_e32 v58, v0
	v_mov_b32_e32 v59, v0
	v_mov_b32_e32 v60, v0
	v_mov_b32_e32 v61, v0
	v_mov_b32_e32 v62, v0
	v_mov_b32_e32 v63, v0
	v_mov_b32_e32 v64, v0
	v_mov_b32_e32 v65, v0
	v_mov_b32_e32 v66, v0
	v_mov_b32_e32 v67, v0
	v_mov_b32_e32 v68, v0
	v_mov_b32_e32 v69, v0
	v_mov_b32_e32 v70, v0
	v_mov_b32_e32 v71, v0
	v_mov_b32_e32 v80, v0
	v_mov_b32_e32 v81, v0
	v_mov_b32_e32 v82, v0
	v_mov_b32_e32 v83, v0
	v_mov_b32_e32 v84, v0
	v_mov_b32_e32 v85, v0
	v_mov_b32_e32 v86, v0
	v_mov_b32_e32 v87, v0
	v_mov_b32_e32 v96, v0
	v_mov_b32_e32 v97, v0
	v_mov_b32_e32 v98, v0
	v_mov_b32_e32 v99, v0
	v_mov_b32_e32 v100, v0
	v_mov_b32_e32 v101, v0
	v_mov_b32_e32 v102, v0
	v_mov_b32_e32 v103, v0
	v_mov_b32_e32 v112, v0
	v_mov_b32_e32 v113, v0
	v_mov_b32_e32 v114, v0
	v_mov_b32_e32 v115, v0
	v_mov_b32_e32 v116, v0
	v_mov_b32_e32 v117, v0
	v_mov_b32_e32 v118, v0
	v_mov_b32_e32 v119, v0
	v_mov_b32_e32 v72, v0
	v_mov_b32_e32 v73, v0
	v_mov_b32_e32 v74, v0
	v_mov_b32_e32 v75, v0
	v_mov_b32_e32 v76, v0
	v_mov_b32_e32 v77, v0
	v_mov_b32_e32 v78, v0
	v_mov_b32_e32 v79, v0
	v_mov_b32_e32 v88, v0
	v_mov_b32_e32 v89, v0
	v_mov_b32_e32 v90, v0
	v_mov_b32_e32 v91, v0
	v_mov_b32_e32 v92, v0
	v_mov_b32_e32 v93, v0
	v_mov_b32_e32 v94, v0
	v_mov_b32_e32 v95, v0
	v_mov_b32_e32 v104, v0
	v_mov_b32_e32 v105, v0
	v_mov_b32_e32 v106, v0
	v_mov_b32_e32 v107, v0
	v_mov_b32_e32 v108, v0
	v_mov_b32_e32 v109, v0
	v_mov_b32_e32 v110, v0
	v_mov_b32_e32 v111, v0
	v_mov_b32_e32 v120, v0
	v_mov_b32_e32 v121, v0
	v_mov_b32_e32 v122, v0
	v_mov_b32_e32 v123, v0
	v_mov_b32_e32 v124, v0
	v_mov_b32_e32 v125, v0
	v_mov_b32_e32 v126, v0
	v_mov_b32_e32 v127, v0
	s_branch .LBB0_1332

.LBB0_1435:
	ds_read_b128 v[128:131], v180
	ds_read_b128 v[132:135], v180 offset:1024
	ds_read_b128 v[136:139], v180 offset:2048
	ds_read_b128 v[140:143], v180 offset:3072
	ds_read_b128 v[144:147], v181
	ds_read_b128 v[148:151], v181 offset:1024
	ds_read_b128 v[170:173], v181 offset:2048
	ds_read_b128 v[174:177], v181 offset:3072
	s_add_u32 s26, s24, 0xfffc0080
	s_addc_u32 s27, s25, -1
	s_cmp_eq_u32 s35, 12
	s_cselect_b32 s29, s1, s27
	s_cselect_b32 s28, s19, s26
	s_cselect_b32 s27, s17, s34
	s_cselect_b32 s26, s30, s31
	v_lshl_add_u64 v[184:185], s[24:25], 0, v[162:163]
	s_add_i32 m0, s40, 0xc000
	s_nop 0
	global_load_lds_dwordx4 v[184:185], off
	v_lshl_add_u64 v[184:185], s[24:25], 0, v[164:165]
	s_add_i32 m0, s40, 0xe000
	s_nop 0
	global_load_lds_dwordx4 v[184:185], off
	ds_read_b128 v[184:187], v182
	ds_read_b128 v[188:191], v182 offset:1024
	ds_read_b128 v[192:195], v182 offset:2048
	ds_read_b128 v[196:199], v182 offset:3072
	ds_read_b128 v[200:203], v182 offset:4096
	ds_read_b128 v[204:207], v182 offset:5120
	ds_read_b128 v[208:211], v182 offset:6144
	ds_read_b128 v[212:215], v182 offset:7168
	s_waitcnt vmcnt(8)
	s_waitcnt lgkmcnt(0)
	s_barrier
	s_setprio 1
	s_waitcnt lgkmcnt(0)
	v_mfma_f32_16x16x32_bf16 v[124:127], v[128:131], v[184:187], v[124:127]
	v_mfma_f32_16x16x32_bf16 v[120:123], v[136:139], v[184:187], v[120:123]
	v_mfma_f32_16x16x32_bf16 v[108:111], v[128:131], v[192:195], v[108:111]
	v_mfma_f32_16x16x32_bf16 v[104:107], v[136:139], v[192:195], v[104:107]
	v_mfma_f32_16x16x32_bf16 v[92:95], v[128:131], v[200:203], v[92:95]
	v_mfma_f32_16x16x32_bf16 v[88:91], v[136:139], v[200:203], v[88:91]
	v_mfma_f32_16x16x32_bf16 v[76:79], v[128:131], v[208:211], v[76:79]
	v_mfma_f32_16x16x32_bf16 v[72:75], v[136:139], v[208:211], v[72:75]
	v_mfma_f32_16x16x32_bf16 v[124:127], v[132:135], v[188:191], v[124:127]
	v_mfma_f32_16x16x32_bf16 v[120:123], v[140:143], v[188:191], v[120:123]
	v_mfma_f32_16x16x32_bf16 v[108:111], v[132:135], v[196:199], v[108:111]
	v_mfma_f32_16x16x32_bf16 v[104:107], v[140:143], v[196:199], v[104:107]
	v_mfma_f32_16x16x32_bf16 v[92:95], v[132:135], v[204:207], v[92:95]
	v_mfma_f32_16x16x32_bf16 v[88:91], v[140:143], v[204:207], v[88:91]
	v_mfma_f32_16x16x32_bf16 v[76:79], v[132:135], v[212:215], v[76:79]
	v_mfma_f32_16x16x32_bf16 v[72:75], v[140:143], v[212:215], v[72:75]
	s_setprio 0
	s_setprio 1
	v_mfma_f32_16x16x32_bf16 v[116:119], v[144:147], v[184:187], v[116:119]
	v_mfma_f32_16x16x32_bf16 v[112:115], v[170:173], v[184:187], v[112:115]
	v_mfma_f32_16x16x32_bf16 v[100:103], v[144:147], v[192:195], v[100:103]
	v_mfma_f32_16x16x32_bf16 v[96:99], v[170:173], v[192:195], v[96:99]
	v_mfma_f32_16x16x32_bf16 v[84:87], v[144:147], v[200:203], v[84:87]
	v_mfma_f32_16x16x32_bf16 v[80:83], v[170:173], v[200:203], v[80:83]
	v_mfma_f32_16x16x32_bf16 v[68:71], v[144:147], v[208:211], v[68:71]
	v_mfma_f32_16x16x32_bf16 v[64:67], v[170:173], v[208:211], v[64:67]
	v_mfma_f32_16x16x32_bf16 v[116:119], v[148:151], v[188:191], v[116:119]
	v_mfma_f32_16x16x32_bf16 v[112:115], v[174:177], v[188:191], v[112:115]
	v_mfma_f32_16x16x32_bf16 v[100:103], v[148:151], v[196:199], v[100:103]
	v_mfma_f32_16x16x32_bf16 v[96:99], v[174:177], v[196:199], v[96:99]
	v_mfma_f32_16x16x32_bf16 v[84:87], v[148:151], v[204:207], v[84:87]
	v_mfma_f32_16x16x32_bf16 v[80:83], v[174:177], v[204:207], v[80:83]
	v_mfma_f32_16x16x32_bf16 v[68:71], v[148:151], v[212:215], v[68:71]
	v_mfma_f32_16x16x32_bf16 v[64:67], v[174:177], v[212:215], v[64:67]
	s_setprio 0
	s_barrier
	s_add_i32 s54, s50, s39
	v_lshl_add_u64 v[216:217], s[26:27], 0, v[154:155]
	s_mov_b32 m0, s54
	v_lshl_add_u64 v[218:219], s[26:27], 0, v[158:159]
	global_load_lds_dwordx4 v[216:217], off
	s_add_i32 m0, s54, 0x2000
	s_add_u32 s54, s26, 0x100000
	s_addc_u32 s55, s27, 0
	s_add_i32 s56, s51, s39
	global_load_lds_dwordx4 v[218:219], off
	v_lshl_add_u64 v[184:185], s[54:55], 0, v[154:155]
	s_mov_b32 m0, s56
	v_lshl_add_u64 v[220:221], s[28:29], 0, v[152:153]
	global_load_lds_dwordx4 v[184:185], off
	v_lshl_add_u64 v[184:185], s[54:55], 0, v[158:159]
	s_add_i32 m0, s56, 0x2000
	v_lshl_add_u64 v[222:223], s[28:29], 0, v[156:157]
	global_load_lds_dwordx4 v[184:185], off
	s_mov_b32 m0, s40
	s_nop 0
	global_load_lds_dwordx4 v[220:221], off
	s_mov_b32 m0, s41
	s_nop 0
	global_load_lds_dwordx4 v[222:223], off
	ds_read_b128 v[184:187], v182 offset:16384
	ds_read_b128 v[188:191], v182 offset:17408
	ds_read_b128 v[192:195], v182 offset:18432
	ds_read_b128 v[196:199], v182 offset:19456
	ds_read_b128 v[200:203], v182 offset:20480
	ds_read_b128 v[204:207], v182 offset:21504
	ds_read_b128 v[208:211], v182 offset:22528
	ds_read_b128 v[212:215], v182 offset:23552
	s_waitcnt vmcnt(8)
	s_waitcnt lgkmcnt(0)
	s_barrier
	s_setprio 1
	s_waitcnt lgkmcnt(0)
	v_mfma_f32_16x16x32_bf16 v[60:63], v[128:131], v[184:187], v[60:63]
	v_mfma_f32_16x16x32_bf16 v[56:59], v[136:139], v[184:187], v[56:59]
	v_mfma_f32_16x16x32_bf16 v[44:47], v[128:131], v[192:195], v[44:47]
	v_mfma_f32_16x16x32_bf16 v[40:43], v[136:139], v[192:195], v[40:43]
	v_mfma_f32_16x16x32_bf16 v[28:31], v[128:131], v[200:203], v[28:31]
	v_mfma_f32_16x16x32_bf16 v[24:27], v[136:139], v[200:203], v[24:27]
	v_mfma_f32_16x16x32_bf16 v[12:15], v[128:131], v[208:211], v[12:15]
	v_mfma_f32_16x16x32_bf16 v[8:11], v[136:139], v[208:211], v[8:11]
	v_mfma_f32_16x16x32_bf16 v[60:63], v[132:135], v[188:191], v[60:63]
	v_mfma_f32_16x16x32_bf16 v[56:59], v[140:143], v[188:191], v[56:59]
	v_mfma_f32_16x16x32_bf16 v[44:47], v[132:135], v[196:199], v[44:47]
	v_mfma_f32_16x16x32_bf16 v[40:43], v[140:143], v[196:199], v[40:43]
	v_mfma_f32_16x16x32_bf16 v[28:31], v[132:135], v[204:207], v[28:31]
	v_mfma_f32_16x16x32_bf16 v[24:27], v[140:143], v[204:207], v[24:27]
	v_mfma_f32_16x16x32_bf16 v[12:15], v[132:135], v[212:215], v[12:15]
	v_mfma_f32_16x16x32_bf16 v[8:11], v[140:143], v[212:215], v[8:11]
	s_setprio 0
	s_setprio 1
	v_mfma_f32_16x16x32_bf16 v[52:55], v[144:147], v[184:187], v[52:55]
	v_mfma_f32_16x16x32_bf16 v[48:51], v[170:173], v[184:187], v[48:51]
	v_mfma_f32_16x16x32_bf16 v[36:39], v[144:147], v[192:195], v[36:39]
	v_mfma_f32_16x16x32_bf16 v[32:35], v[170:173], v[192:195], v[32:35]
	v_mfma_f32_16x16x32_bf16 v[20:23], v[144:147], v[200:203], v[20:23]
	v_mfma_f32_16x16x32_bf16 v[16:19], v[170:173], v[200:203], v[16:19]
	v_mfma_f32_16x16x32_bf16 v[4:7], v[144:147], v[208:211], v[4:7]
	v_mfma_f32_16x16x32_bf16 v[0:3], v[170:173], v[208:211], v[0:3]
	v_mfma_f32_16x16x32_bf16 v[52:55], v[148:151], v[188:191], v[52:55]
	v_mfma_f32_16x16x32_bf16 v[48:51], v[174:177], v[188:191], v[48:51]
	v_mfma_f32_16x16x32_bf16 v[36:39], v[148:151], v[196:199], v[36:39]
	v_mfma_f32_16x16x32_bf16 v[32:35], v[174:177], v[196:199], v[32:35]
	v_mfma_f32_16x16x32_bf16 v[20:23], v[148:151], v[204:207], v[20:23]
	v_mfma_f32_16x16x32_bf16 v[16:19], v[174:177], v[204:207], v[16:19]
	v_mfma_f32_16x16x32_bf16 v[4:7], v[148:151], v[212:215], v[4:7]
	v_mfma_f32_16x16x32_bf16 v[0:3], v[174:177], v[212:215], v[0:3]
	s_setprio 0
	s_barrier
	s_add_i32 s54, 0, 0x18000
	s_add_i32 s55, 0, 0x1c000
	v_add_u32_e32 v140, s54, v178
	v_add_u32_e32 v174, s55, v178
	ds_read_b128 v[128:131], v140
	ds_read_b128 v[132:135], v140 offset:1024
	ds_read_b128 v[136:139], v140 offset:2048
	ds_read_b128 v[140:143], v140 offset:3072
	ds_read_b128 v[144:147], v174
	ds_read_b128 v[148:151], v174 offset:1024
	ds_read_b128 v[170:173], v174 offset:2048
	ds_read_b128 v[174:177], v174 offset:3072
	s_add_u32 s28, s28, 0x40000
	s_addc_u32 s29, s29, 0
	s_mov_b32 m0, s42
	v_lshl_add_u64 v[184:185], s[28:29], 0, v[152:153]
	global_load_lds_dwordx4 v[184:185], off
	v_lshl_add_u64 v[184:185], s[28:29], 0, v[156:157]
	s_mov_b32 m0, s43
	s_nop 0
	global_load_lds_dwordx4 v[184:185], off
	ds_read_b128 v[184:187], v182 offset:32768
	ds_read_b128 v[188:191], v182 offset:33792
	ds_read_b128 v[192:195], v182 offset:34816
	ds_read_b128 v[196:199], v182 offset:35840
	ds_read_b128 v[200:203], v182 offset:36864
	ds_read_b128 v[204:207], v182 offset:37888
	ds_read_b128 v[208:211], v182 offset:38912
	ds_read_b128 v[212:215], v182 offset:39936
	s_waitcnt vmcnt(8)
	s_waitcnt lgkmcnt(0)
	s_barrier
	s_setprio 1
	s_waitcnt lgkmcnt(0)
	v_mfma_f32_16x16x32_bf16 v[124:127], v[128:131], v[184:187], v[124:127]
	v_mfma_f32_16x16x32_bf16 v[120:123], v[136:139], v[184:187], v[120:123]
	v_mfma_f32_16x16x32_bf16 v[108:111], v[128:131], v[192:195], v[108:111]
	v_mfma_f32_16x16x32_bf16 v[104:107], v[136:139], v[192:195], v[104:107]
	v_mfma_f32_16x16x32_bf16 v[92:95], v[128:131], v[200:203], v[92:95]
	v_mfma_f32_16x16x32_bf16 v[88:91], v[136:139], v[200:203], v[88:91]
	v_mfma_f32_16x16x32_bf16 v[76:79], v[128:131], v[208:211], v[76:79]
	v_mfma_f32_16x16x32_bf16 v[72:75], v[136:139], v[208:211], v[72:75]
	v_mfma_f32_16x16x32_bf16 v[124:127], v[132:135], v[188:191], v[124:127]
	v_mfma_f32_16x16x32_bf16 v[120:123], v[140:143], v[188:191], v[120:123]
	v_mfma_f32_16x16x32_bf16 v[108:111], v[132:135], v[196:199], v[108:111]
	v_mfma_f32_16x16x32_bf16 v[104:107], v[140:143], v[196:199], v[104:107]
	v_mfma_f32_16x16x32_bf16 v[92:95], v[132:135], v[204:207], v[92:95]
	v_mfma_f32_16x16x32_bf16 v[88:91], v[140:143], v[204:207], v[88:91]
	v_mfma_f32_16x16x32_bf16 v[76:79], v[132:135], v[212:215], v[76:79]
	v_mfma_f32_16x16x32_bf16 v[72:75], v[140:143], v[212:215], v[72:75]
	s_setprio 0
	s_setprio 1
	v_mfma_f32_16x16x32_bf16 v[116:119], v[144:147], v[184:187], v[116:119]
	v_mfma_f32_16x16x32_bf16 v[112:115], v[170:173], v[184:187], v[112:115]
	v_mfma_f32_16x16x32_bf16 v[100:103], v[144:147], v[192:195], v[100:103]
	v_mfma_f32_16x16x32_bf16 v[96:99], v[170:173], v[192:195], v[96:99]
	v_mfma_f32_16x16x32_bf16 v[84:87], v[144:147], v[200:203], v[84:87]
	v_mfma_f32_16x16x32_bf16 v[80:83], v[170:173], v[200:203], v[80:83]
	v_mfma_f32_16x16x32_bf16 v[68:71], v[144:147], v[208:211], v[68:71]
	v_mfma_f32_16x16x32_bf16 v[64:67], v[170:173], v[208:211], v[64:67]
	v_mfma_f32_16x16x32_bf16 v[116:119], v[148:151], v[188:191], v[116:119]
	v_mfma_f32_16x16x32_bf16 v[112:115], v[174:177], v[188:191], v[112:115]
	v_mfma_f32_16x16x32_bf16 v[100:103], v[148:151], v[196:199], v[100:103]
	v_mfma_f32_16x16x32_bf16 v[96:99], v[174:177], v[196:199], v[96:99]
	v_mfma_f32_16x16x32_bf16 v[84:87], v[148:151], v[204:207], v[84:87]
	v_mfma_f32_16x16x32_bf16 v[80:83], v[174:177], v[204:207], v[80:83]
	v_mfma_f32_16x16x32_bf16 v[68:71], v[148:151], v[212:215], v[68:71]
	v_mfma_f32_16x16x32_bf16 v[64:67], v[174:177], v[212:215], v[64:67]
	s_setprio 0
	s_barrier
	s_add_i32 s28, s54, s39
	v_lshl_add_u64 v[184:185], v[216:217], 0, s[14:15]
	s_mov_b32 m0, s28
	s_nop 0
	global_load_lds_dwordx4 v[184:185], off
	s_add_i32 m0, s28, 0x2000
	s_add_u32 s26, s26, 0x100080
	v_lshl_add_u64 v[184:185], v[218:219], 0, s[14:15]
	s_addc_u32 s27, s27, 0
	s_add_i32 s28, s55, s39
	global_load_lds_dwordx4 v[184:185], off
	v_lshl_add_u64 v[184:185], s[26:27], 0, v[154:155]
	s_mov_b32 m0, s28
	s_nop 0
	global_load_lds_dwordx4 v[184:185], off
	v_lshl_add_u64 v[184:185], s[26:27], 0, v[158:159]
	s_add_i32 m0, s28, 0x2000
	s_nop 0
	global_load_lds_dwordx4 v[184:185], off
	v_lshl_add_u64 v[184:185], v[220:221], 0, s[14:15]
	s_mov_b32 m0, s45
	s_nop 0
	global_load_lds_dwordx4 v[184:185], off
	v_lshl_add_u64 v[184:185], v[222:223], 0, s[14:15]
	s_mov_b32 m0, s46
	s_nop 0
	global_load_lds_dwordx4 v[184:185], off
	ds_read_b128 v[184:187], v182 offset:49152
	ds_read_b128 v[188:191], v182 offset:50176
	ds_read_b128 v[192:195], v182 offset:51200
	ds_read_b128 v[196:199], v182 offset:52224
	ds_read_b128 v[200:203], v182 offset:53248
	ds_read_b128 v[204:207], v182 offset:54272
	ds_read_b128 v[208:211], v182 offset:55296
	ds_read_b128 v[212:215], v182 offset:56320
	s_waitcnt vmcnt(8)
	s_waitcnt lgkmcnt(0)
	s_barrier
	s_setprio 1
	s_waitcnt lgkmcnt(0)
	v_mfma_f32_16x16x32_bf16 v[60:63], v[128:131], v[184:187], v[60:63]
	v_mfma_f32_16x16x32_bf16 v[56:59], v[136:139], v[184:187], v[56:59]
	v_mfma_f32_16x16x32_bf16 v[44:47], v[128:131], v[192:195], v[44:47]
	v_mfma_f32_16x16x32_bf16 v[40:43], v[136:139], v[192:195], v[40:43]
	v_mfma_f32_16x16x32_bf16 v[28:31], v[128:131], v[200:203], v[28:31]
	v_mfma_f32_16x16x32_bf16 v[24:27], v[136:139], v[200:203], v[24:27]
	v_mfma_f32_16x16x32_bf16 v[12:15], v[128:131], v[208:211], v[12:15]
	v_mfma_f32_16x16x32_bf16 v[8:11], v[136:139], v[208:211], v[8:11]
	v_mfma_f32_16x16x32_bf16 v[60:63], v[132:135], v[188:191], v[60:63]
	v_mfma_f32_16x16x32_bf16 v[56:59], v[140:143], v[188:191], v[56:59]
	v_mfma_f32_16x16x32_bf16 v[44:47], v[132:135], v[196:199], v[44:47]
	v_mfma_f32_16x16x32_bf16 v[40:43], v[140:143], v[196:199], v[40:43]
	v_mfma_f32_16x16x32_bf16 v[28:31], v[132:135], v[204:207], v[28:31]
	v_mfma_f32_16x16x32_bf16 v[24:27], v[140:143], v[204:207], v[24:27]
	v_mfma_f32_16x16x32_bf16 v[12:15], v[132:135], v[212:215], v[12:15]
	v_mfma_f32_16x16x32_bf16 v[8:11], v[140:143], v[212:215], v[8:11]
	s_setprio 0
	s_setprio 1
	v_mfma_f32_16x16x32_bf16 v[52:55], v[144:147], v[184:187], v[52:55]
	v_mfma_f32_16x16x32_bf16 v[48:51], v[170:173], v[184:187], v[48:51]
	v_mfma_f32_16x16x32_bf16 v[36:39], v[144:147], v[192:195], v[36:39]
	v_mfma_f32_16x16x32_bf16 v[32:35], v[170:173], v[192:195], v[32:35]
	v_mfma_f32_16x16x32_bf16 v[20:23], v[144:147], v[200:203], v[20:23]
	v_mfma_f32_16x16x32_bf16 v[16:19], v[170:173], v[200:203], v[16:19]
	v_mfma_f32_16x16x32_bf16 v[4:7], v[144:147], v[208:211], v[4:7]
	v_mfma_f32_16x16x32_bf16 v[0:3], v[170:173], v[208:211], v[0:3]
	v_mfma_f32_16x16x32_bf16 v[52:55], v[148:151], v[188:191], v[52:55]
	v_mfma_f32_16x16x32_bf16 v[48:51], v[174:177], v[188:191], v[48:51]
	v_mfma_f32_16x16x32_bf16 v[36:39], v[148:151], v[196:199], v[36:39]
	v_mfma_f32_16x16x32_bf16 v[32:35], v[174:177], v[196:199], v[32:35]
	v_mfma_f32_16x16x32_bf16 v[20:23], v[148:151], v[204:207], v[20:23]
	v_mfma_f32_16x16x32_bf16 v[16:19], v[174:177], v[204:207], v[16:19]
	v_mfma_f32_16x16x32_bf16 v[4:7], v[148:151], v[212:215], v[4:7]
	v_mfma_f32_16x16x32_bf16 v[0:3], v[174:177], v[212:215], v[0:3]
	s_setprio 0
	s_barrier
	s_add_i32 s35, s35, 2
	s_add_u32 s24, s24, 0x100
	s_addc_u32 s25, s25, 0
	s_add_u32 s31, s31, 0x100
	s_addc_u32 s34, s34, 0
	s_cmp_gt_u32 s35, 13
	s_cbranch_scc0 .LBB0_1435
	s_and_b64 vcc, exec, s[8:9]
	s_cbranch_vccz .LBB0_1438
	s_barrier

.LBB0_1543:
	ds_read_b128 v[128:131], v167
	ds_read_b128 v[154:157], v167 offset:1024
	ds_read_b128 v[172:175], v167 offset:2048
	ds_read_b128 v[176:179], v167 offset:3072
	ds_read_b128 v[180:183], v168
	ds_read_b128 v[184:187], v168 offset:1024
	ds_read_b128 v[188:191], v168 offset:2048
	ds_read_b128 v[192:195], v168 offset:3072
	s_add_u32 s22, s20, 0x1000
	s_addc_u32 s23, s21, 0
	s_cmp_eq_u32 s54, 60
	s_cselect_b32 s27, s13, s23
	s_cselect_b32 s26, s50, s22
	s_cselect_b32 s25, s11, s53
	s_cselect_b32 s24, s51, s52
	v_lshl_add_u64 v[160:161], s[20:21], 0, v[144:145]
	s_add_i32 m0, s19, 0xc000
	s_nop 0
	global_load_lds_dwordx4 v[160:161], off
	v_lshl_add_u64 v[160:161], s[20:21], 0, v[146:147]
	s_add_i32 m0, s19, 0xe000
	s_nop 0
	global_load_lds_dwordx4 v[160:161], off
	ds_read_b128 v[196:199], v169
	ds_read_b128 v[200:203], v169 offset:1024
	ds_read_b128 v[204:207], v169 offset:2048
	ds_read_b128 v[208:211], v169 offset:3072
	ds_read_b128 v[212:215], v169 offset:4096
	ds_read_b128 v[216:219], v169 offset:5120
	ds_read_b128 v[220:223], v169 offset:6144
	ds_read_b128 v[224:227], v169 offset:7168
	s_waitcnt vmcnt(8)
	s_waitcnt lgkmcnt(0)
	s_barrier
	s_setprio 1
	s_waitcnt lgkmcnt(0)
	v_mfma_f32_16x16x32_bf16 v[124:127], v[128:131], v[196:199], v[124:127]
	v_mfma_f32_16x16x32_bf16 v[120:123], v[172:175], v[196:199], v[120:123]
	v_mfma_f32_16x16x32_bf16 v[108:111], v[128:131], v[204:207], v[108:111]
	v_mfma_f32_16x16x32_bf16 v[104:107], v[172:175], v[204:207], v[104:107]
	v_mfma_f32_16x16x32_bf16 v[92:95], v[128:131], v[212:215], v[92:95]
	v_mfma_f32_16x16x32_bf16 v[88:91], v[172:175], v[212:215], v[88:91]
	v_mfma_f32_16x16x32_bf16 v[76:79], v[128:131], v[220:223], v[76:79]
	v_mfma_f32_16x16x32_bf16 v[72:75], v[172:175], v[220:223], v[72:75]
	v_mfma_f32_16x16x32_bf16 v[124:127], v[154:157], v[200:203], v[124:127]
	v_mfma_f32_16x16x32_bf16 v[120:123], v[176:179], v[200:203], v[120:123]
	v_mfma_f32_16x16x32_bf16 v[108:111], v[154:157], v[208:211], v[108:111]
	v_mfma_f32_16x16x32_bf16 v[104:107], v[176:179], v[208:211], v[104:107]
	v_mfma_f32_16x16x32_bf16 v[92:95], v[154:157], v[216:219], v[92:95]
	v_mfma_f32_16x16x32_bf16 v[88:91], v[176:179], v[216:219], v[88:91]
	v_mfma_f32_16x16x32_bf16 v[76:79], v[154:157], v[224:227], v[76:79]
	v_mfma_f32_16x16x32_bf16 v[72:75], v[176:179], v[224:227], v[72:75]
	s_setprio 0
	s_setprio 1
	v_mfma_f32_16x16x32_bf16 v[116:119], v[180:183], v[196:199], v[116:119]
	v_mfma_f32_16x16x32_bf16 v[112:115], v[188:191], v[196:199], v[112:115]
	v_mfma_f32_16x16x32_bf16 v[100:103], v[180:183], v[204:207], v[100:103]
	v_mfma_f32_16x16x32_bf16 v[96:99], v[188:191], v[204:207], v[96:99]
	v_mfma_f32_16x16x32_bf16 v[84:87], v[180:183], v[212:215], v[84:87]
	v_mfma_f32_16x16x32_bf16 v[80:83], v[188:191], v[212:215], v[80:83]
	v_mfma_f32_16x16x32_bf16 v[68:71], v[180:183], v[220:223], v[68:71]
	v_mfma_f32_16x16x32_bf16 v[64:67], v[188:191], v[220:223], v[64:67]
	v_mfma_f32_16x16x32_bf16 v[116:119], v[184:187], v[200:203], v[116:119]
	v_mfma_f32_16x16x32_bf16 v[112:115], v[192:195], v[200:203], v[112:115]
	v_mfma_f32_16x16x32_bf16 v[100:103], v[184:187], v[208:211], v[100:103]
	v_mfma_f32_16x16x32_bf16 v[96:99], v[192:195], v[208:211], v[96:99]
	v_mfma_f32_16x16x32_bf16 v[84:87], v[184:187], v[216:219], v[84:87]
	v_mfma_f32_16x16x32_bf16 v[80:83], v[192:195], v[216:219], v[80:83]
	v_mfma_f32_16x16x32_bf16 v[68:71], v[184:187], v[224:227], v[68:71]
	v_mfma_f32_16x16x32_bf16 v[64:67], v[192:195], v[224:227], v[64:67]
	s_setprio 0
	s_barrier
	s_add_i32 s20, s45, s30
	v_lshl_add_u64 v[160:161], s[24:25], 0, v[134:135]
	s_mov_b32 m0, s20
	v_lshl_add_u64 v[164:165], s[24:25], 0, v[138:139]
	global_load_lds_dwordx4 v[160:161], off
	s_add_i32 m0, s20, 0x2000
	s_add_u32 s20, s24, 0x100000
	s_addc_u32 s21, s25, 0
	s_add_i32 s55, s46, s30
	global_load_lds_dwordx4 v[164:165], off
	v_lshl_add_u64 v[196:197], s[20:21], 0, v[134:135]
	s_mov_b32 m0, s55
	v_lshl_add_u64 v[228:229], s[26:27], 0, v[132:133]
	global_load_lds_dwordx4 v[196:197], off
	v_lshl_add_u64 v[196:197], s[20:21], 0, v[138:139]
	s_add_i32 m0, s55, 0x2000
	v_lshl_add_u64 v[230:231], s[26:27], 0, v[136:137]
	global_load_lds_dwordx4 v[196:197], off
	s_mov_b32 m0, s19
	s_nop 0
	global_load_lds_dwordx4 v[228:229], off
	s_mov_b32 m0, s36
	s_nop 0
	global_load_lds_dwordx4 v[230:231], off
	ds_read_b128 v[196:199], v169 offset:16384
	ds_read_b128 v[200:203], v169 offset:17408
	ds_read_b128 v[204:207], v169 offset:18432
	ds_read_b128 v[208:211], v169 offset:19456
	ds_read_b128 v[212:215], v169 offset:20480
	ds_read_b128 v[216:219], v169 offset:21504
	ds_read_b128 v[220:223], v169 offset:22528
	ds_read_b128 v[224:227], v169 offset:23552
	s_waitcnt vmcnt(8)
	s_waitcnt lgkmcnt(0)
	s_barrier
	s_setprio 1
	s_waitcnt lgkmcnt(0)
	v_mfma_f32_16x16x32_bf16 v[60:63], v[128:131], v[196:199], v[60:63]
	v_mfma_f32_16x16x32_bf16 v[56:59], v[172:175], v[196:199], v[56:59]
	v_mfma_f32_16x16x32_bf16 v[44:47], v[128:131], v[204:207], v[44:47]
	v_mfma_f32_16x16x32_bf16 v[40:43], v[172:175], v[204:207], v[40:43]
	v_mfma_f32_16x16x32_bf16 v[28:31], v[128:131], v[212:215], v[28:31]
	v_mfma_f32_16x16x32_bf16 v[24:27], v[172:175], v[212:215], v[24:27]
	v_mfma_f32_16x16x32_bf16 v[12:15], v[128:131], v[220:223], v[12:15]
	v_mfma_f32_16x16x32_bf16 v[8:11], v[172:175], v[220:223], v[8:11]
	v_mfma_f32_16x16x32_bf16 v[60:63], v[154:157], v[200:203], v[60:63]
	v_mfma_f32_16x16x32_bf16 v[56:59], v[176:179], v[200:203], v[56:59]
	v_mfma_f32_16x16x32_bf16 v[44:47], v[154:157], v[208:211], v[44:47]
	v_mfma_f32_16x16x32_bf16 v[40:43], v[176:179], v[208:211], v[40:43]
	v_mfma_f32_16x16x32_bf16 v[28:31], v[154:157], v[216:219], v[28:31]
	v_mfma_f32_16x16x32_bf16 v[24:27], v[176:179], v[216:219], v[24:27]
	v_mfma_f32_16x16x32_bf16 v[12:15], v[154:157], v[224:227], v[12:15]
	v_mfma_f32_16x16x32_bf16 v[8:11], v[176:179], v[224:227], v[8:11]
	s_setprio 0
	s_setprio 1
	v_mfma_f32_16x16x32_bf16 v[52:55], v[180:183], v[196:199], v[52:55]
	v_mfma_f32_16x16x32_bf16 v[48:51], v[188:191], v[196:199], v[48:51]
	v_mfma_f32_16x16x32_bf16 v[36:39], v[180:183], v[204:207], v[36:39]
	v_mfma_f32_16x16x32_bf16 v[32:35], v[188:191], v[204:207], v[32:35]
	v_mfma_f32_16x16x32_bf16 v[20:23], v[180:183], v[212:215], v[20:23]
	v_mfma_f32_16x16x32_bf16 v[16:19], v[188:191], v[212:215], v[16:19]
	v_mfma_f32_16x16x32_bf16 v[4:7], v[180:183], v[220:223], v[4:7]
	v_mfma_f32_16x16x32_bf16 v[0:3], v[188:191], v[220:223], v[0:3]
	v_mfma_f32_16x16x32_bf16 v[52:55], v[184:187], v[200:203], v[52:55]
	v_mfma_f32_16x16x32_bf16 v[48:51], v[192:195], v[200:203], v[48:51]
	v_mfma_f32_16x16x32_bf16 v[36:39], v[184:187], v[208:211], v[36:39]
	v_mfma_f32_16x16x32_bf16 v[32:35], v[192:195], v[208:211], v[32:35]
	v_mfma_f32_16x16x32_bf16 v[20:23], v[184:187], v[216:219], v[20:23]
	v_mfma_f32_16x16x32_bf16 v[16:19], v[192:195], v[216:219], v[16:19]
	v_mfma_f32_16x16x32_bf16 v[4:7], v[184:187], v[224:227], v[4:7]
	v_mfma_f32_16x16x32_bf16 v[0:3], v[192:195], v[224:227], v[0:3]
	s_setprio 0
	s_barrier
	s_add_i32 s55, 0, 0x18000
	v_add_u32_e32 v153, s55, v159
	s_add_i32 s56, 0, 0x1c000
	ds_read_b128 v[128:131], v153
	ds_read_b128 v[154:157], v153 offset:1024
	ds_read_b128 v[172:175], v153 offset:2048
	ds_read_b128 v[176:179], v153 offset:3072
	v_add_u32_e32 v153, s56, v159
	ds_read_b128 v[180:183], v153
	ds_read_b128 v[184:187], v153 offset:1024
	ds_read_b128 v[188:191], v153 offset:2048
	ds_read_b128 v[192:195], v153 offset:3072
	s_add_u32 s20, s26, 0x100000
	s_addc_u32 s21, s27, 0
	s_mov_b32 m0, s37
	v_lshl_add_u64 v[196:197], s[20:21], 0, v[132:133]
	global_load_lds_dwordx4 v[196:197], off
	v_lshl_add_u64 v[196:197], s[20:21], 0, v[136:137]
	s_mov_b32 m0, s38
	s_nop 0
	global_load_lds_dwordx4 v[196:197], off
	ds_read_b128 v[196:199], v169 offset:32768
	ds_read_b128 v[200:203], v169 offset:33792
	ds_read_b128 v[204:207], v169 offset:34816
	ds_read_b128 v[208:211], v169 offset:35840
	ds_read_b128 v[212:215], v169 offset:36864
	ds_read_b128 v[216:219], v169 offset:37888
	ds_read_b128 v[220:223], v169 offset:38912
	ds_read_b128 v[224:227], v169 offset:39936
	s_waitcnt vmcnt(8)
	s_waitcnt lgkmcnt(0)
	s_barrier
	s_setprio 1
	s_waitcnt lgkmcnt(0)
	v_mfma_f32_16x16x32_bf16 v[124:127], v[128:131], v[196:199], v[124:127]
	v_mfma_f32_16x16x32_bf16 v[120:123], v[172:175], v[196:199], v[120:123]
	v_mfma_f32_16x16x32_bf16 v[108:111], v[128:131], v[204:207], v[108:111]
	v_mfma_f32_16x16x32_bf16 v[104:107], v[172:175], v[204:207], v[104:107]
	v_mfma_f32_16x16x32_bf16 v[92:95], v[128:131], v[212:215], v[92:95]
	v_mfma_f32_16x16x32_bf16 v[88:91], v[172:175], v[212:215], v[88:91]
	v_mfma_f32_16x16x32_bf16 v[76:79], v[128:131], v[220:223], v[76:79]
	v_mfma_f32_16x16x32_bf16 v[72:75], v[172:175], v[220:223], v[72:75]
	v_mfma_f32_16x16x32_bf16 v[124:127], v[154:157], v[200:203], v[124:127]
	v_mfma_f32_16x16x32_bf16 v[120:123], v[176:179], v[200:203], v[120:123]
	v_mfma_f32_16x16x32_bf16 v[108:111], v[154:157], v[208:211], v[108:111]
	v_mfma_f32_16x16x32_bf16 v[104:107], v[176:179], v[208:211], v[104:107]
	v_mfma_f32_16x16x32_bf16 v[92:95], v[154:157], v[216:219], v[92:95]
	v_mfma_f32_16x16x32_bf16 v[88:91], v[176:179], v[216:219], v[88:91]
	v_mfma_f32_16x16x32_bf16 v[76:79], v[154:157], v[224:227], v[76:79]
	v_mfma_f32_16x16x32_bf16 v[72:75], v[176:179], v[224:227], v[72:75]
	s_setprio 0
	s_setprio 1
	v_mfma_f32_16x16x32_bf16 v[116:119], v[180:183], v[196:199], v[116:119]
	v_mfma_f32_16x16x32_bf16 v[112:115], v[188:191], v[196:199], v[112:115]
	v_mfma_f32_16x16x32_bf16 v[100:103], v[180:183], v[204:207], v[100:103]
	v_mfma_f32_16x16x32_bf16 v[96:99], v[188:191], v[204:207], v[96:99]
	v_mfma_f32_16x16x32_bf16 v[84:87], v[180:183], v[212:215], v[84:87]
	v_mfma_f32_16x16x32_bf16 v[80:83], v[188:191], v[212:215], v[80:83]
	v_mfma_f32_16x16x32_bf16 v[68:71], v[180:183], v[220:223], v[68:71]
	v_mfma_f32_16x16x32_bf16 v[64:67], v[188:191], v[220:223], v[64:67]
	v_mfma_f32_16x16x32_bf16 v[116:119], v[184:187], v[200:203], v[116:119]
	v_mfma_f32_16x16x32_bf16 v[112:115], v[192:195], v[200:203], v[112:115]
	v_mfma_f32_16x16x32_bf16 v[100:103], v[184:187], v[208:211], v[100:103]
	v_mfma_f32_16x16x32_bf16 v[96:99], v[192:195], v[208:211], v[96:99]
	v_mfma_f32_16x16x32_bf16 v[84:87], v[184:187], v[216:219], v[84:87]
	v_mfma_f32_16x16x32_bf16 v[80:83], v[192:195], v[216:219], v[80:83]
	v_mfma_f32_16x16x32_bf16 v[68:71], v[184:187], v[224:227], v[68:71]
	v_mfma_f32_16x16x32_bf16 v[64:67], v[192:195], v[224:227], v[64:67]
	s_setprio 0
	s_barrier
	s_add_i32 s20, s55, s30
	v_lshl_add_u64 v[160:161], v[160:161], 0, s[8:9]
	s_mov_b32 m0, s20
	s_nop 0
	global_load_lds_dwordx4 v[160:161], off
	s_add_i32 m0, s20, 0x2000
	s_add_u32 s20, s24, 0x100800
	v_lshl_add_u64 v[160:161], v[164:165], 0, s[8:9]
	s_addc_u32 s21, s25, 0
	s_add_i32 s24, s56, s30
	global_load_lds_dwordx4 v[160:161], off
	v_lshl_add_u64 v[160:161], s[20:21], 0, v[134:135]
	s_mov_b32 m0, s24
	s_nop 0
	global_load_lds_dwordx4 v[160:161], off
	v_lshl_add_u64 v[160:161], s[20:21], 0, v[138:139]
	s_add_i32 m0, s24, 0x2000
	s_nop 0
	global_load_lds_dwordx4 v[160:161], off
	v_lshl_add_u64 v[160:161], v[228:229], 0, s[8:9]
	s_mov_b32 m0, s41
	s_nop 0
	global_load_lds_dwordx4 v[160:161], off
	v_lshl_add_u64 v[160:161], v[230:231], 0, s[8:9]
	s_mov_b32 m0, s42
	s_nop 0
	global_load_lds_dwordx4 v[160:161], off
	ds_read_b128 v[196:199], v169 offset:49152
	ds_read_b128 v[200:203], v169 offset:50176
	ds_read_b128 v[204:207], v169 offset:51200
	ds_read_b128 v[208:211], v169 offset:52224
	ds_read_b128 v[212:215], v169 offset:53248
	ds_read_b128 v[216:219], v169 offset:54272
	ds_read_b128 v[220:223], v169 offset:55296
	ds_read_b128 v[224:227], v169 offset:56320
	s_waitcnt vmcnt(8)
	s_waitcnt lgkmcnt(0)
	s_barrier
	s_setprio 1
	s_waitcnt lgkmcnt(0)
	v_mfma_f32_16x16x32_bf16 v[60:63], v[128:131], v[196:199], v[60:63]
	v_mfma_f32_16x16x32_bf16 v[56:59], v[172:175], v[196:199], v[56:59]
	v_mfma_f32_16x16x32_bf16 v[44:47], v[128:131], v[204:207], v[44:47]
	v_mfma_f32_16x16x32_bf16 v[40:43], v[172:175], v[204:207], v[40:43]
	v_mfma_f32_16x16x32_bf16 v[28:31], v[128:131], v[212:215], v[28:31]
	v_mfma_f32_16x16x32_bf16 v[24:27], v[172:175], v[212:215], v[24:27]
	v_mfma_f32_16x16x32_bf16 v[12:15], v[128:131], v[220:223], v[12:15]
	v_mfma_f32_16x16x32_bf16 v[8:11], v[172:175], v[220:223], v[8:11]
	v_mfma_f32_16x16x32_bf16 v[60:63], v[154:157], v[200:203], v[60:63]
	v_mfma_f32_16x16x32_bf16 v[56:59], v[176:179], v[200:203], v[56:59]
	v_mfma_f32_16x16x32_bf16 v[44:47], v[154:157], v[208:211], v[44:47]
	v_mfma_f32_16x16x32_bf16 v[40:43], v[176:179], v[208:211], v[40:43]
	v_mfma_f32_16x16x32_bf16 v[28:31], v[154:157], v[216:219], v[28:31]
	v_mfma_f32_16x16x32_bf16 v[24:27], v[176:179], v[216:219], v[24:27]
	v_mfma_f32_16x16x32_bf16 v[12:15], v[154:157], v[224:227], v[12:15]
	v_mfma_f32_16x16x32_bf16 v[8:11], v[176:179], v[224:227], v[8:11]
	s_setprio 0
	s_setprio 1
	v_mfma_f32_16x16x32_bf16 v[52:55], v[180:183], v[196:199], v[52:55]
	v_mfma_f32_16x16x32_bf16 v[48:51], v[188:191], v[196:199], v[48:51]
	v_mfma_f32_16x16x32_bf16 v[36:39], v[180:183], v[204:207], v[36:39]
	v_mfma_f32_16x16x32_bf16 v[32:35], v[188:191], v[204:207], v[32:35]
	v_mfma_f32_16x16x32_bf16 v[20:23], v[180:183], v[212:215], v[20:23]
	v_mfma_f32_16x16x32_bf16 v[16:19], v[188:191], v[212:215], v[16:19]
	v_mfma_f32_16x16x32_bf16 v[4:7], v[180:183], v[220:223], v[4:7]
	v_mfma_f32_16x16x32_bf16 v[0:3], v[188:191], v[220:223], v[0:3]
	v_mfma_f32_16x16x32_bf16 v[52:55], v[184:187], v[200:203], v[52:55]
	v_mfma_f32_16x16x32_bf16 v[48:51], v[192:195], v[200:203], v[48:51]
	v_mfma_f32_16x16x32_bf16 v[36:39], v[184:187], v[208:211], v[36:39]
	v_mfma_f32_16x16x32_bf16 v[32:35], v[192:195], v[208:211], v[32:35]
	v_mfma_f32_16x16x32_bf16 v[20:23], v[184:187], v[216:219], v[20:23]
	v_mfma_f32_16x16x32_bf16 v[16:19], v[192:195], v[216:219], v[16:19]
	v_mfma_f32_16x16x32_bf16 v[4:7], v[184:187], v[224:227], v[4:7]
	v_mfma_f32_16x16x32_bf16 v[0:3], v[192:195], v[224:227], v[0:3]
	s_setprio 0
	s_barrier
	s_add_i32 s54, s54, 2
	s_add_u32 s52, s52, 0x1000
	s_addc_u32 s53, s53, 0
	s_cmp_gt_u32 s54, 61
	s_mov_b64 s[20:21], s[22:23]
	s_cbranch_scc0 .LBB0_1543
	s_and_b64 vcc, exec, s[4:5]
	s_cbranch_vccz .LBB0_1546
	s_barrier

.LBB0_1625:
	ds_read_b128 v[128:131], v177
	ds_read_b128 v[132:135], v177 offset:1024
	ds_read_b128 v[136:139], v177 offset:2048
	ds_read_b128 v[140:143], v177 offset:3072
	ds_read_b128 v[144:147], v178
	ds_read_b128 v[148:151], v178 offset:1024
	ds_read_b128 v[170:173], v178 offset:2048
	ds_read_b128 v[182:185], v178 offset:3072
	s_add_u32 s24, s22, 0xffc00800
	s_addc_u32 s25, s23, -1
	s_cmpk_eq_i32 s57, 0xfc
	s_cselect_b32 s27, s29, s25
	s_cselect_b32 s26, s53, s24
	s_cselect_b32 s25, s17, s56
	s_cselect_b32 s24, s54, s55
	v_lshl_add_u64 v[186:187], s[22:23], 0, v[162:163]
	s_add_i32 m0, s38, 0xc000
	s_nop 0
	global_load_lds_dwordx4 v[186:187], off
	v_lshl_add_u64 v[186:187], s[22:23], 0, v[164:165]
	s_add_i32 m0, s38, 0xe000
	s_nop 0
	global_load_lds_dwordx4 v[186:187], off
	ds_read_b128 v[186:189], v179
	ds_read_b128 v[190:193], v179 offset:1024
	ds_read_b128 v[194:197], v179 offset:2048
	ds_read_b128 v[198:201], v179 offset:3072
	ds_read_b128 v[202:205], v179 offset:4096
	ds_read_b128 v[206:209], v179 offset:5120
	ds_read_b128 v[210:213], v179 offset:6144
	ds_read_b128 v[214:217], v179 offset:7168
	s_waitcnt vmcnt(8)
	s_waitcnt lgkmcnt(0)
	s_barrier
	s_setprio 1
	s_waitcnt lgkmcnt(0)
	v_mfma_f32_16x16x32_bf16 v[124:127], v[128:131], v[186:189], v[124:127]
	v_mfma_f32_16x16x32_bf16 v[120:123], v[136:139], v[186:189], v[120:123]
	v_mfma_f32_16x16x32_bf16 v[108:111], v[128:131], v[194:197], v[108:111]
	v_mfma_f32_16x16x32_bf16 v[104:107], v[136:139], v[194:197], v[104:107]
	v_mfma_f32_16x16x32_bf16 v[92:95], v[128:131], v[202:205], v[92:95]
	v_mfma_f32_16x16x32_bf16 v[88:91], v[136:139], v[202:205], v[88:91]
	v_mfma_f32_16x16x32_bf16 v[76:79], v[128:131], v[210:213], v[76:79]
	v_mfma_f32_16x16x32_bf16 v[72:75], v[136:139], v[210:213], v[72:75]
	v_mfma_f32_16x16x32_bf16 v[124:127], v[132:135], v[190:193], v[124:127]
	v_mfma_f32_16x16x32_bf16 v[120:123], v[140:143], v[190:193], v[120:123]
	v_mfma_f32_16x16x32_bf16 v[108:111], v[132:135], v[198:201], v[108:111]
	v_mfma_f32_16x16x32_bf16 v[104:107], v[140:143], v[198:201], v[104:107]
	v_mfma_f32_16x16x32_bf16 v[92:95], v[132:135], v[206:209], v[92:95]
	v_mfma_f32_16x16x32_bf16 v[88:91], v[140:143], v[206:209], v[88:91]
	v_mfma_f32_16x16x32_bf16 v[76:79], v[132:135], v[214:217], v[76:79]
	v_mfma_f32_16x16x32_bf16 v[72:75], v[140:143], v[214:217], v[72:75]
	s_setprio 0
	s_setprio 1
	v_mfma_f32_16x16x32_bf16 v[116:119], v[144:147], v[186:189], v[116:119]
	v_mfma_f32_16x16x32_bf16 v[112:115], v[170:173], v[186:189], v[112:115]
	v_mfma_f32_16x16x32_bf16 v[100:103], v[144:147], v[194:197], v[100:103]
	v_mfma_f32_16x16x32_bf16 v[96:99], v[170:173], v[194:197], v[96:99]
	v_mfma_f32_16x16x32_bf16 v[84:87], v[144:147], v[202:205], v[84:87]
	v_mfma_f32_16x16x32_bf16 v[80:83], v[170:173], v[202:205], v[80:83]
	v_mfma_f32_16x16x32_bf16 v[68:71], v[144:147], v[210:213], v[68:71]
	v_mfma_f32_16x16x32_bf16 v[64:67], v[170:173], v[210:213], v[64:67]
	v_mfma_f32_16x16x32_bf16 v[116:119], v[148:151], v[190:193], v[116:119]
	v_mfma_f32_16x16x32_bf16 v[112:115], v[182:185], v[190:193], v[112:115]
	v_mfma_f32_16x16x32_bf16 v[100:103], v[148:151], v[198:201], v[100:103]
	v_mfma_f32_16x16x32_bf16 v[96:99], v[182:185], v[198:201], v[96:99]
	v_mfma_f32_16x16x32_bf16 v[84:87], v[148:151], v[206:209], v[84:87]
	v_mfma_f32_16x16x32_bf16 v[80:83], v[182:185], v[206:209], v[80:83]
	v_mfma_f32_16x16x32_bf16 v[68:71], v[148:151], v[214:217], v[68:71]
	v_mfma_f32_16x16x32_bf16 v[64:67], v[182:185], v[214:217], v[64:67]
	s_setprio 0
	s_barrier
	s_add_i32 s58, s48, s37
	v_lshl_add_u64 v[218:219], s[24:25], 0, v[154:155]
	s_mov_b32 m0, s58
	v_lshl_add_u64 v[220:221], s[24:25], 0, v[158:159]
	global_load_lds_dwordx4 v[218:219], off
	s_add_i32 m0, s58, 0x2000
	s_add_u32 s58, s24, 0x400000
	s_addc_u32 s59, s25, 0
	s_add_i32 s60, s49, s37
	global_load_lds_dwordx4 v[220:221], off
	v_lshl_add_u64 v[186:187], s[58:59], 0, v[154:155]
	s_mov_b32 m0, s60
	v_lshl_add_u64 v[222:223], s[26:27], 0, v[152:153]
	global_load_lds_dwordx4 v[186:187], off
	v_lshl_add_u64 v[186:187], s[58:59], 0, v[158:159]
	s_add_i32 m0, s60, 0x2000
	v_lshl_add_u64 v[224:225], s[26:27], 0, v[156:157]
	global_load_lds_dwordx4 v[186:187], off
	s_mov_b32 m0, s38
	s_nop 0
	global_load_lds_dwordx4 v[222:223], off
	s_mov_b32 m0, s39
	s_nop 0
	global_load_lds_dwordx4 v[224:225], off
	ds_read_b128 v[186:189], v179 offset:16384
	ds_read_b128 v[190:193], v179 offset:17408
	ds_read_b128 v[194:197], v179 offset:18432
	ds_read_b128 v[198:201], v179 offset:19456
	ds_read_b128 v[202:205], v179 offset:20480
	ds_read_b128 v[206:209], v179 offset:21504
	ds_read_b128 v[210:213], v179 offset:22528
	ds_read_b128 v[214:217], v179 offset:23552
	s_waitcnt vmcnt(8)
	s_waitcnt lgkmcnt(0)
	s_barrier
	s_setprio 1
	s_waitcnt lgkmcnt(0)
	v_mfma_f32_16x16x32_bf16 v[60:63], v[128:131], v[186:189], v[60:63]
	v_mfma_f32_16x16x32_bf16 v[56:59], v[136:139], v[186:189], v[56:59]
	v_mfma_f32_16x16x32_bf16 v[44:47], v[128:131], v[194:197], v[44:47]
	v_mfma_f32_16x16x32_bf16 v[40:43], v[136:139], v[194:197], v[40:43]
	v_mfma_f32_16x16x32_bf16 v[28:31], v[128:131], v[202:205], v[28:31]
	v_mfma_f32_16x16x32_bf16 v[24:27], v[136:139], v[202:205], v[24:27]
	v_mfma_f32_16x16x32_bf16 v[12:15], v[128:131], v[210:213], v[12:15]
	v_mfma_f32_16x16x32_bf16 v[8:11], v[136:139], v[210:213], v[8:11]
	v_mfma_f32_16x16x32_bf16 v[60:63], v[132:135], v[190:193], v[60:63]
	v_mfma_f32_16x16x32_bf16 v[56:59], v[140:143], v[190:193], v[56:59]
	v_mfma_f32_16x16x32_bf16 v[44:47], v[132:135], v[198:201], v[44:47]
	v_mfma_f32_16x16x32_bf16 v[40:43], v[140:143], v[198:201], v[40:43]
	v_mfma_f32_16x16x32_bf16 v[28:31], v[132:135], v[206:209], v[28:31]
	v_mfma_f32_16x16x32_bf16 v[24:27], v[140:143], v[206:209], v[24:27]
	v_mfma_f32_16x16x32_bf16 v[12:15], v[132:135], v[214:217], v[12:15]
	v_mfma_f32_16x16x32_bf16 v[8:11], v[140:143], v[214:217], v[8:11]
	s_setprio 0
	s_setprio 1
	v_mfma_f32_16x16x32_bf16 v[52:55], v[144:147], v[186:189], v[52:55]
	v_mfma_f32_16x16x32_bf16 v[48:51], v[170:173], v[186:189], v[48:51]
	v_mfma_f32_16x16x32_bf16 v[36:39], v[144:147], v[194:197], v[36:39]
	v_mfma_f32_16x16x32_bf16 v[32:35], v[170:173], v[194:197], v[32:35]
	v_mfma_f32_16x16x32_bf16 v[20:23], v[144:147], v[202:205], v[20:23]
	v_mfma_f32_16x16x32_bf16 v[16:19], v[170:173], v[202:205], v[16:19]
	v_mfma_f32_16x16x32_bf16 v[4:7], v[144:147], v[210:213], v[4:7]
	v_mfma_f32_16x16x32_bf16 v[0:3], v[170:173], v[210:213], v[0:3]
	v_mfma_f32_16x16x32_bf16 v[52:55], v[148:151], v[190:193], v[52:55]
	v_mfma_f32_16x16x32_bf16 v[48:51], v[182:185], v[190:193], v[48:51]
	v_mfma_f32_16x16x32_bf16 v[36:39], v[148:151], v[198:201], v[36:39]
	v_mfma_f32_16x16x32_bf16 v[32:35], v[182:185], v[198:201], v[32:35]
	v_mfma_f32_16x16x32_bf16 v[20:23], v[148:151], v[206:209], v[20:23]
	v_mfma_f32_16x16x32_bf16 v[16:19], v[182:185], v[206:209], v[16:19]
	v_mfma_f32_16x16x32_bf16 v[4:7], v[148:151], v[214:217], v[4:7]
	v_mfma_f32_16x16x32_bf16 v[0:3], v[182:185], v[214:217], v[0:3]
	s_setprio 0
	s_barrier
	s_add_i32 s58, 0, 0x18000
	s_add_i32 s59, 0, 0x1c000
	v_add_u32_e32 v140, s58, v174
	v_add_u32_e32 v181, s59, v174
	ds_read_b128 v[128:131], v140
	ds_read_b128 v[132:135], v140 offset:1024
	ds_read_b128 v[136:139], v140 offset:2048
	ds_read_b128 v[140:143], v140 offset:3072
	ds_read_b128 v[144:147], v181
	ds_read_b128 v[148:151], v181 offset:1024
	ds_read_b128 v[170:173], v181 offset:2048
	ds_read_b128 v[182:185], v181 offset:3072
	s_add_u32 s26, s26, 0x400000
	s_addc_u32 s27, s27, 0
	s_mov_b32 m0, s40
	v_lshl_add_u64 v[186:187], s[26:27], 0, v[152:153]
	global_load_lds_dwordx4 v[186:187], off
	v_lshl_add_u64 v[186:187], s[26:27], 0, v[156:157]
	s_mov_b32 m0, s41
	s_nop 0
	global_load_lds_dwordx4 v[186:187], off
	ds_read_b128 v[186:189], v179 offset:32768
	ds_read_b128 v[190:193], v179 offset:33792
	ds_read_b128 v[194:197], v179 offset:34816
	ds_read_b128 v[198:201], v179 offset:35840
	ds_read_b128 v[202:205], v179 offset:36864
	ds_read_b128 v[206:209], v179 offset:37888
	ds_read_b128 v[210:213], v179 offset:38912
	ds_read_b128 v[214:217], v179 offset:39936
	s_waitcnt vmcnt(8)
	s_waitcnt lgkmcnt(0)
	s_barrier
	s_setprio 1
	s_waitcnt lgkmcnt(0)
	v_mfma_f32_16x16x32_bf16 v[124:127], v[128:131], v[186:189], v[124:127]
	v_mfma_f32_16x16x32_bf16 v[120:123], v[136:139], v[186:189], v[120:123]
	v_mfma_f32_16x16x32_bf16 v[108:111], v[128:131], v[194:197], v[108:111]
	v_mfma_f32_16x16x32_bf16 v[104:107], v[136:139], v[194:197], v[104:107]
	v_mfma_f32_16x16x32_bf16 v[92:95], v[128:131], v[202:205], v[92:95]
	v_mfma_f32_16x16x32_bf16 v[88:91], v[136:139], v[202:205], v[88:91]
	v_mfma_f32_16x16x32_bf16 v[76:79], v[128:131], v[210:213], v[76:79]
	v_mfma_f32_16x16x32_bf16 v[72:75], v[136:139], v[210:213], v[72:75]
	v_mfma_f32_16x16x32_bf16 v[124:127], v[132:135], v[190:193], v[124:127]
	v_mfma_f32_16x16x32_bf16 v[120:123], v[140:143], v[190:193], v[120:123]
	v_mfma_f32_16x16x32_bf16 v[108:111], v[132:135], v[198:201], v[108:111]
	v_mfma_f32_16x16x32_bf16 v[104:107], v[140:143], v[198:201], v[104:107]
	v_mfma_f32_16x16x32_bf16 v[92:95], v[132:135], v[206:209], v[92:95]
	v_mfma_f32_16x16x32_bf16 v[88:91], v[140:143], v[206:209], v[88:91]
	v_mfma_f32_16x16x32_bf16 v[76:79], v[132:135], v[214:217], v[76:79]
	v_mfma_f32_16x16x32_bf16 v[72:75], v[140:143], v[214:217], v[72:75]
	s_setprio 0
	s_setprio 1
	v_mfma_f32_16x16x32_bf16 v[116:119], v[144:147], v[186:189], v[116:119]
	v_mfma_f32_16x16x32_bf16 v[112:115], v[170:173], v[186:189], v[112:115]
	v_mfma_f32_16x16x32_bf16 v[100:103], v[144:147], v[194:197], v[100:103]
	v_mfma_f32_16x16x32_bf16 v[96:99], v[170:173], v[194:197], v[96:99]
	v_mfma_f32_16x16x32_bf16 v[84:87], v[144:147], v[202:205], v[84:87]
	v_mfma_f32_16x16x32_bf16 v[80:83], v[170:173], v[202:205], v[80:83]
	v_mfma_f32_16x16x32_bf16 v[68:71], v[144:147], v[210:213], v[68:71]
	v_mfma_f32_16x16x32_bf16 v[64:67], v[170:173], v[210:213], v[64:67]
	v_mfma_f32_16x16x32_bf16 v[116:119], v[148:151], v[190:193], v[116:119]
	v_mfma_f32_16x16x32_bf16 v[112:115], v[182:185], v[190:193], v[112:115]
	v_mfma_f32_16x16x32_bf16 v[100:103], v[148:151], v[198:201], v[100:103]
	v_mfma_f32_16x16x32_bf16 v[96:99], v[182:185], v[198:201], v[96:99]
	v_mfma_f32_16x16x32_bf16 v[84:87], v[148:151], v[206:209], v[84:87]
	v_mfma_f32_16x16x32_bf16 v[80:83], v[182:185], v[206:209], v[80:83]
	v_mfma_f32_16x16x32_bf16 v[68:71], v[148:151], v[214:217], v[68:71]
	v_mfma_f32_16x16x32_bf16 v[64:67], v[182:185], v[214:217], v[64:67]
	s_setprio 0
	s_barrier
	s_add_i32 s26, s58, s37
	v_lshl_add_u64 v[186:187], v[218:219], 0, s[14:15]
	s_mov_b32 m0, s26
	s_nop 0
	global_load_lds_dwordx4 v[186:187], off
	s_add_i32 m0, s26, 0x2000
	s_add_u32 s24, s24, 0x400800
	v_lshl_add_u64 v[186:187], v[220:221], 0, s[14:15]
	s_addc_u32 s25, s25, 0
	s_add_i32 s26, s59, s37
	global_load_lds_dwordx4 v[186:187], off
	v_lshl_add_u64 v[186:187], s[24:25], 0, v[154:155]
	s_mov_b32 m0, s26
	s_nop 0
	global_load_lds_dwordx4 v[186:187], off
	v_lshl_add_u64 v[186:187], s[24:25], 0, v[158:159]
	s_add_i32 m0, s26, 0x2000
	s_nop 0
	global_load_lds_dwordx4 v[186:187], off
	v_lshl_add_u64 v[186:187], v[222:223], 0, s[14:15]
	s_mov_b32 m0, s43
	s_nop 0
	global_load_lds_dwordx4 v[186:187], off
	v_lshl_add_u64 v[186:187], v[224:225], 0, s[14:15]
	s_mov_b32 m0, s44
	s_nop 0
	global_load_lds_dwordx4 v[186:187], off
	ds_read_b128 v[186:189], v179 offset:49152
	ds_read_b128 v[190:193], v179 offset:50176
	ds_read_b128 v[194:197], v179 offset:51200
	ds_read_b128 v[198:201], v179 offset:52224
	ds_read_b128 v[202:205], v179 offset:53248
	ds_read_b128 v[206:209], v179 offset:54272
	ds_read_b128 v[210:213], v179 offset:55296
	ds_read_b128 v[214:217], v179 offset:56320
	s_waitcnt vmcnt(8)
	s_waitcnt lgkmcnt(0)
	s_barrier
	s_setprio 1
	s_waitcnt lgkmcnt(0)
	v_mfma_f32_16x16x32_bf16 v[60:63], v[128:131], v[186:189], v[60:63]
	v_mfma_f32_16x16x32_bf16 v[56:59], v[136:139], v[186:189], v[56:59]
	v_mfma_f32_16x16x32_bf16 v[44:47], v[128:131], v[194:197], v[44:47]
	v_mfma_f32_16x16x32_bf16 v[40:43], v[136:139], v[194:197], v[40:43]
	v_mfma_f32_16x16x32_bf16 v[28:31], v[128:131], v[202:205], v[28:31]
	v_mfma_f32_16x16x32_bf16 v[24:27], v[136:139], v[202:205], v[24:27]
	v_mfma_f32_16x16x32_bf16 v[12:15], v[128:131], v[210:213], v[12:15]
	v_mfma_f32_16x16x32_bf16 v[8:11], v[136:139], v[210:213], v[8:11]
	v_mfma_f32_16x16x32_bf16 v[60:63], v[132:135], v[190:193], v[60:63]
	v_mfma_f32_16x16x32_bf16 v[56:59], v[140:143], v[190:193], v[56:59]
	v_mfma_f32_16x16x32_bf16 v[44:47], v[132:135], v[198:201], v[44:47]
	v_mfma_f32_16x16x32_bf16 v[40:43], v[140:143], v[198:201], v[40:43]
	v_mfma_f32_16x16x32_bf16 v[28:31], v[132:135], v[206:209], v[28:31]
	v_mfma_f32_16x16x32_bf16 v[24:27], v[140:143], v[206:209], v[24:27]
	v_mfma_f32_16x16x32_bf16 v[12:15], v[132:135], v[214:217], v[12:15]
	v_mfma_f32_16x16x32_bf16 v[8:11], v[140:143], v[214:217], v[8:11]
	s_setprio 0
	s_setprio 1
	v_mfma_f32_16x16x32_bf16 v[52:55], v[144:147], v[186:189], v[52:55]
	v_mfma_f32_16x16x32_bf16 v[48:51], v[170:173], v[186:189], v[48:51]
	v_mfma_f32_16x16x32_bf16 v[36:39], v[144:147], v[194:197], v[36:39]
	v_mfma_f32_16x16x32_bf16 v[32:35], v[170:173], v[194:197], v[32:35]
	v_mfma_f32_16x16x32_bf16 v[20:23], v[144:147], v[202:205], v[20:23]
	v_mfma_f32_16x16x32_bf16 v[16:19], v[170:173], v[202:205], v[16:19]
	v_mfma_f32_16x16x32_bf16 v[4:7], v[144:147], v[210:213], v[4:7]
	v_mfma_f32_16x16x32_bf16 v[0:3], v[170:173], v[210:213], v[0:3]
	v_mfma_f32_16x16x32_bf16 v[52:55], v[148:151], v[190:193], v[52:55]
	v_mfma_f32_16x16x32_bf16 v[48:51], v[182:185], v[190:193], v[48:51]
	v_mfma_f32_16x16x32_bf16 v[36:39], v[148:151], v[198:201], v[36:39]
	v_mfma_f32_16x16x32_bf16 v[32:35], v[182:185], v[198:201], v[32:35]
	v_mfma_f32_16x16x32_bf16 v[20:23], v[148:151], v[206:209], v[20:23]
	v_mfma_f32_16x16x32_bf16 v[16:19], v[182:185], v[206:209], v[16:19]
	v_mfma_f32_16x16x32_bf16 v[4:7], v[148:151], v[214:217], v[4:7]
	v_mfma_f32_16x16x32_bf16 v[0:3], v[182:185], v[214:217], v[0:3]
	s_setprio 0
	s_barrier
	s_add_i32 s57, s57, 2
	s_add_u32 s22, s22, 0x1000
	s_addc_u32 s23, s23, 0
	s_add_u32 s55, s55, 0x1000
	s_addc_u32 s56, s56, 0
	s_cmpk_gt_u32 s57, 0xfd
	s_cbranch_scc0 .LBB0_1625
	s_and_b64 vcc, exec, s[6:7]
	s_cbranch_vccz .LBB0_1628
	s_barrier
